# CV1/CV2: each weight row read once chip-wide (4 rows x 16 batches per wave), sc1 result stores, global arrival counter polled at P5 entry
# baseline (speedup 1.0000x reference)
.LBB0_443:
	v_readlane_b32 s0, v254, 8
	v_readlane_b32 s1, v254, 9
	v_readlane_b32 s2, v254, 20
	v_mbcnt_lo_u32_b32 v0, -1, 0
	v_mbcnt_hi_u32_b32 v0, -1, v0
	s_and_b32 s3, s2, 7
	s_lshl_b32 s5, s2, 3
	s_add_i32 s5, s5, s69
	v_lshlrev_b32_e32 v1, 5, v0
	v_lshlrev_b32_e32 v4, 6, v0
	s_cmpk_lt_u32 s5, 0x7c0
	s_cbranch_scc0 .Lcv7_idle
	s_add_i32 s8, s5, 0xfffffdc0
	s_mov_b32 s10, 0x2100000
	s_mov_b32 s11, 0x3200000
	s_mov_b32 s22, 0x3e00000
	s_mov_b32 s23, 0x3d00000
	s_movk_i32 s28, 0x1600
	s_movk_i32 s29, 0x900
	s_movk_i32 s4, 0x6000
	s_movk_i32 s9, 0x3000
	s_cmpk_lt_u32 s5, 0x240
	s_cselect_b32 s8, s5, s8
	s_cselect_b32 s10, s11, s10
	s_cselect_b32 s22, s23, s22
	s_cselect_b32 s23, s29, s28
	s_cselect_b32 s4, s9, s4
	s_lshl_b32 s91, s8, 2
	s_lshl_b32 s8, s8, 13
	s_add_u32 s28, s0, s10
	s_addc_u32 s29, s1, 0
	s_add_u32 s28, s28, s8
	s_addc_u32 s29, s29, 0
	global_load_dwordx4 v[162:165], v1, s[28:29]
	global_load_dwordx4 v[166:169], v1, s[28:29] offset:16
	global_load_dwordx4 v[170:173], v1, s[28:29] offset:2048
	global_load_dwordx4 v[174:177], v1, s[28:29] offset:2064
	s_add_u32 s28, s28, 0x1000
	s_addc_u32 s29, s29, 0
	global_load_dwordx4 v[178:181], v1, s[28:29]
	global_load_dwordx4 v[182:185], v1, s[28:29] offset:16
	global_load_dwordx4 v[186:189], v1, s[28:29] offset:2048
	global_load_dwordx4 v[190:193], v1, s[28:29] offset:2064
	s_add_u32 s10, s0, 0x100000
	s_addc_u32 s11, s1, 0
	s_add_u32 s10, s10, s4
	s_addc_u32 s11, s11, 0
	global_load_dwordx4 v[194:197], v4, s[10:11]
	global_load_dwordx4 v[198:201], v4, s[10:11] offset:16
	global_load_dwordx4 v[202:205], v4, s[10:11] offset:32
	global_load_dwordx4 v[206:209], v4, s[10:11] offset:48
	s_add_u32 s10, s10, 0x9000
	s_addc_u32 s11, s11, 0
	global_load_dwordx4 v[226:229], v4, s[10:11]
	global_load_dwordx4 v[230:233], v4, s[10:11] offset:16
	global_load_dwordx4 v[234:237], v4, s[10:11] offset:32
	global_load_dwordx4 v[238:241], v4, s[10:11] offset:48
	s_add_u32 s10, s10, 0x9000
	s_addc_u32 s11, s11, 0
	s_waitcnt vmcnt(8)
	s_lshl_b32 s8, s3, 8
	s_add_u32 s8, s0, s8
	s_addc_u32 s9, s1, 0
	v_mov_b32_e32 v15, 0
	v_mov_b32_e32 v11, 1
	s_mov_b64 exec, 1
	global_atomic_add v15, v11, s[8:9] offset:2112
	s_mov_b64 exec, -1
	v_lshlrev_b32_e32 v16, 16, v162
	v_and_b32_e32 v17, 0xffff0000, v162
	v_lshlrev_b32_e32 v18, 16, v163
	v_and_b32_e32 v19, 0xffff0000, v163
	v_lshlrev_b32_e32 v20, 16, v164
	v_and_b32_e32 v21, 0xffff0000, v164
	v_lshlrev_b32_e32 v22, 16, v165
	v_and_b32_e32 v23, 0xffff0000, v165
	v_lshlrev_b32_e32 v24, 16, v166
	v_and_b32_e32 v25, 0xffff0000, v166
	v_lshlrev_b32_e32 v26, 16, v167
	v_and_b32_e32 v27, 0xffff0000, v167
	v_lshlrev_b32_e32 v28, 16, v168
	v_and_b32_e32 v29, 0xffff0000, v168
	v_lshlrev_b32_e32 v30, 16, v169
	v_and_b32_e32 v31, 0xffff0000, v169
	v_lshlrev_b32_e32 v32, 16, v170
	v_and_b32_e32 v33, 0xffff0000, v170
	v_lshlrev_b32_e32 v34, 16, v171
	v_and_b32_e32 v35, 0xffff0000, v171
	v_lshlrev_b32_e32 v36, 16, v172
	v_and_b32_e32 v37, 0xffff0000, v172
	v_lshlrev_b32_e32 v38, 16, v173
	v_and_b32_e32 v39, 0xffff0000, v173
	v_lshlrev_b32_e32 v40, 16, v174
	v_and_b32_e32 v41, 0xffff0000, v174
	v_lshlrev_b32_e32 v42, 16, v175
	v_and_b32_e32 v43, 0xffff0000, v175
	v_lshlrev_b32_e32 v44, 16, v176
	v_and_b32_e32 v45, 0xffff0000, v176
	v_lshlrev_b32_e32 v46, 16, v177
	v_and_b32_e32 v47, 0xffff0000, v177
	v_lshlrev_b32_e32 v48, 16, v178
	v_and_b32_e32 v49, 0xffff0000, v178
	v_lshlrev_b32_e32 v50, 16, v179
	v_and_b32_e32 v51, 0xffff0000, v179
	v_lshlrev_b32_e32 v52, 16, v180
	v_and_b32_e32 v53, 0xffff0000, v180
	v_lshlrev_b32_e32 v54, 16, v181
	v_and_b32_e32 v55, 0xffff0000, v181
	v_lshlrev_b32_e32 v56, 16, v182
	v_and_b32_e32 v57, 0xffff0000, v182
	v_lshlrev_b32_e32 v58, 16, v183
	v_and_b32_e32 v59, 0xffff0000, v183
	v_lshlrev_b32_e32 v60, 16, v184
	v_and_b32_e32 v61, 0xffff0000, v184
	v_lshlrev_b32_e32 v62, 16, v185
	v_and_b32_e32 v63, 0xffff0000, v185
	v_lshlrev_b32_e32 v64, 16, v186
	v_and_b32_e32 v65, 0xffff0000, v186
	v_lshlrev_b32_e32 v211, 16, v187
	v_and_b32_e32 v212, 0xffff0000, v187
	v_lshlrev_b32_e32 v213, 16, v188
	v_and_b32_e32 v214, 0xffff0000, v188
	v_lshlrev_b32_e32 v215, 16, v189
	v_and_b32_e32 v216, 0xffff0000, v189
	v_lshlrev_b32_e32 v217, 16, v190
	v_and_b32_e32 v218, 0xffff0000, v190
	v_lshlrev_b32_e32 v219, 16, v191
	v_and_b32_e32 v220, 0xffff0000, v191
	v_lshlrev_b32_e32 v221, 16, v192
	v_and_b32_e32 v222, 0xffff0000, v192
	v_lshlrev_b32_e32 v223, 16, v193
	v_and_b32_e32 v224, 0xffff0000, v193
	global_load_dwordx4 v[162:165], v4, s[10:11]
	global_load_dwordx4 v[166:169], v4, s[10:11] offset:16
	global_load_dwordx4 v[170:173], v4, s[10:11] offset:32
	global_load_dwordx4 v[174:177], v4, s[10:11] offset:48
	s_add_u32 s10, s10, 0x9000
	s_addc_u32 s11, s11, 0
	global_load_dwordx4 v[178:181], v4, s[10:11]
	global_load_dwordx4 v[182:185], v4, s[10:11] offset:16
	global_load_dwordx4 v[186:189], v4, s[10:11] offset:32
	global_load_dwordx4 v[190:193], v4, s[10:11] offset:48
	s_add_u32 s10, s10, 0x9000
	s_addc_u32 s11, s11, 0
	s_waitcnt vmcnt(8)
	v_mul_f32_e32 v98, v194, v16
	v_mul_f32_e32 v99, v194, v32
	v_mul_f32_e32 v100, v194, v48
	v_mul_f32_e32 v101, v194, v64
	v_mul_f32_e32 v102, v226, v16
	v_mul_f32_e32 v103, v226, v32
	v_mul_f32_e32 v104, v226, v48
	v_mul_f32_e32 v105, v226, v64
	v_fmac_f32_e32 v98, v195, v17
	v_fmac_f32_e32 v99, v195, v33
	v_fmac_f32_e32 v100, v195, v49
	v_fmac_f32_e32 v101, v195, v65
	v_fmac_f32_e32 v102, v227, v17
	v_fmac_f32_e32 v103, v227, v33
	v_fmac_f32_e32 v104, v227, v49
	v_fmac_f32_e32 v105, v227, v65
	v_fmac_f32_e32 v98, v196, v18
	v_fmac_f32_e32 v99, v196, v34
	v_fmac_f32_e32 v100, v196, v50
	v_fmac_f32_e32 v101, v196, v211
	v_fmac_f32_e32 v102, v228, v18
	v_fmac_f32_e32 v103, v228, v34
	v_fmac_f32_e32 v104, v228, v50
	v_fmac_f32_e32 v105, v228, v211
	v_fmac_f32_e32 v98, v197, v19
	v_fmac_f32_e32 v99, v197, v35
	v_fmac_f32_e32 v100, v197, v51
	v_fmac_f32_e32 v101, v197, v212
	v_fmac_f32_e32 v102, v229, v19
	v_fmac_f32_e32 v103, v229, v35
	v_fmac_f32_e32 v104, v229, v51
	v_fmac_f32_e32 v105, v229, v212
	v_fmac_f32_e32 v98, v198, v20
	v_fmac_f32_e32 v99, v198, v36
	v_fmac_f32_e32 v100, v198, v52
	v_fmac_f32_e32 v101, v198, v213
	v_fmac_f32_e32 v102, v230, v20
	v_fmac_f32_e32 v103, v230, v36
	v_fmac_f32_e32 v104, v230, v52
	v_fmac_f32_e32 v105, v230, v213
	v_fmac_f32_e32 v98, v199, v21
	v_fmac_f32_e32 v99, v199, v37
	v_fmac_f32_e32 v100, v199, v53
	v_fmac_f32_e32 v101, v199, v214
	v_fmac_f32_e32 v102, v231, v21
	v_fmac_f32_e32 v103, v231, v37
	v_fmac_f32_e32 v104, v231, v53
	v_fmac_f32_e32 v105, v231, v214
	v_fmac_f32_e32 v98, v200, v22
	v_fmac_f32_e32 v99, v200, v38
	v_fmac_f32_e32 v100, v200, v54
	v_fmac_f32_e32 v101, v200, v215
	v_fmac_f32_e32 v102, v232, v22
	v_fmac_f32_e32 v103, v232, v38
	v_fmac_f32_e32 v104, v232, v54
	v_fmac_f32_e32 v105, v232, v215
	v_fmac_f32_e32 v98, v201, v23
	v_fmac_f32_e32 v99, v201, v39
	v_fmac_f32_e32 v100, v201, v55
	v_fmac_f32_e32 v101, v201, v216
	v_fmac_f32_e32 v102, v233, v23
	v_fmac_f32_e32 v103, v233, v39
	v_fmac_f32_e32 v104, v233, v55
	v_fmac_f32_e32 v105, v233, v216
	v_fmac_f32_e32 v98, v202, v24
	v_fmac_f32_e32 v99, v202, v40
	v_fmac_f32_e32 v100, v202, v56
	v_fmac_f32_e32 v101, v202, v217
	v_fmac_f32_e32 v102, v234, v24
	v_fmac_f32_e32 v103, v234, v40
	v_fmac_f32_e32 v104, v234, v56
	v_fmac_f32_e32 v105, v234, v217
	v_fmac_f32_e32 v98, v203, v25
	v_fmac_f32_e32 v99, v203, v41
	v_fmac_f32_e32 v100, v203, v57
	v_fmac_f32_e32 v101, v203, v218
	v_fmac_f32_e32 v102, v235, v25
	v_fmac_f32_e32 v103, v235, v41
	v_fmac_f32_e32 v104, v235, v57
	v_fmac_f32_e32 v105, v235, v218
	v_fmac_f32_e32 v98, v204, v26
	v_fmac_f32_e32 v99, v204, v42
	v_fmac_f32_e32 v100, v204, v58
	v_fmac_f32_e32 v101, v204, v219
	v_fmac_f32_e32 v102, v236, v26
	v_fmac_f32_e32 v103, v236, v42
	v_fmac_f32_e32 v104, v236, v58
	v_fmac_f32_e32 v105, v236, v219
	v_fmac_f32_e32 v98, v205, v27
	v_fmac_f32_e32 v99, v205, v43
	v_fmac_f32_e32 v100, v205, v59
	v_fmac_f32_e32 v101, v205, v220
	v_fmac_f32_e32 v102, v237, v27
	v_fmac_f32_e32 v103, v237, v43
	v_fmac_f32_e32 v104, v237, v59
	v_fmac_f32_e32 v105, v237, v220
	v_fmac_f32_e32 v98, v206, v28
	v_fmac_f32_e32 v99, v206, v44
	v_fmac_f32_e32 v100, v206, v60
	v_fmac_f32_e32 v101, v206, v221
	v_fmac_f32_e32 v102, v238, v28
	v_fmac_f32_e32 v103, v238, v44
	v_fmac_f32_e32 v104, v238, v60
	v_fmac_f32_e32 v105, v238, v221
	v_fmac_f32_e32 v98, v207, v29
	v_fmac_f32_e32 v99, v207, v45
	v_fmac_f32_e32 v100, v207, v61
	v_fmac_f32_e32 v101, v207, v222
	v_fmac_f32_e32 v102, v239, v29
	v_fmac_f32_e32 v103, v239, v45
	v_fmac_f32_e32 v104, v239, v61
	v_fmac_f32_e32 v105, v239, v222
	v_fmac_f32_e32 v98, v208, v30
	v_fmac_f32_e32 v99, v208, v46
	v_fmac_f32_e32 v100, v208, v62
	v_fmac_f32_e32 v101, v208, v223
	v_fmac_f32_e32 v102, v240, v30
	v_fmac_f32_e32 v103, v240, v46
	v_fmac_f32_e32 v104, v240, v62
	v_fmac_f32_e32 v105, v240, v223
	v_fmac_f32_e32 v98, v209, v31
	v_fmac_f32_e32 v99, v209, v47
	v_fmac_f32_e32 v100, v209, v63
	v_fmac_f32_e32 v101, v209, v224
	v_fmac_f32_e32 v102, v241, v31
	v_fmac_f32_e32 v103, v241, v47
	v_fmac_f32_e32 v104, v241, v63
	v_fmac_f32_e32 v105, v241, v224
	global_load_dwordx4 v[194:197], v4, s[10:11]
	global_load_dwordx4 v[198:201], v4, s[10:11] offset:16
	global_load_dwordx4 v[202:205], v4, s[10:11] offset:32
	global_load_dwordx4 v[206:209], v4, s[10:11] offset:48
	s_add_u32 s10, s10, 0x9000
	s_addc_u32 s11, s11, 0
	global_load_dwordx4 v[226:229], v4, s[10:11]
	global_load_dwordx4 v[230:233], v4, s[10:11] offset:16
	global_load_dwordx4 v[234:237], v4, s[10:11] offset:32
	global_load_dwordx4 v[238:241], v4, s[10:11] offset:48
	s_add_u32 s10, s10, 0x9000
	s_addc_u32 s11, s11, 0
	s_waitcnt vmcnt(8)
	v_mul_f32_e32 v106, v162, v16
	v_mul_f32_e32 v107, v162, v32
	v_mul_f32_e32 v108, v162, v48
	v_mul_f32_e32 v109, v162, v64
	v_mul_f32_e32 v110, v178, v16
	v_mul_f32_e32 v111, v178, v32
	v_mul_f32_e32 v112, v178, v48
	v_mul_f32_e32 v113, v178, v64
	v_fmac_f32_e32 v106, v163, v17
	v_fmac_f32_e32 v107, v163, v33
	v_fmac_f32_e32 v108, v163, v49
	v_fmac_f32_e32 v109, v163, v65
	v_fmac_f32_e32 v110, v179, v17
	v_fmac_f32_e32 v111, v179, v33
	v_fmac_f32_e32 v112, v179, v49
	v_fmac_f32_e32 v113, v179, v65
	v_fmac_f32_e32 v106, v164, v18
	v_fmac_f32_e32 v107, v164, v34
	v_fmac_f32_e32 v108, v164, v50
	v_fmac_f32_e32 v109, v164, v211
	v_fmac_f32_e32 v110, v180, v18
	v_fmac_f32_e32 v111, v180, v34
	v_fmac_f32_e32 v112, v180, v50
	v_fmac_f32_e32 v113, v180, v211
	v_fmac_f32_e32 v106, v165, v19
	v_fmac_f32_e32 v107, v165, v35
	v_fmac_f32_e32 v108, v165, v51
	v_fmac_f32_e32 v109, v165, v212
	v_fmac_f32_e32 v110, v181, v19
	v_fmac_f32_e32 v111, v181, v35
	v_fmac_f32_e32 v112, v181, v51
	v_fmac_f32_e32 v113, v181, v212
	v_fmac_f32_e32 v106, v166, v20
	v_fmac_f32_e32 v107, v166, v36
	v_fmac_f32_e32 v108, v166, v52
	v_fmac_f32_e32 v109, v166, v213
	v_fmac_f32_e32 v110, v182, v20
	v_fmac_f32_e32 v111, v182, v36
	v_fmac_f32_e32 v112, v182, v52
	v_fmac_f32_e32 v113, v182, v213
	v_fmac_f32_e32 v106, v167, v21
	v_fmac_f32_e32 v107, v167, v37
	v_fmac_f32_e32 v108, v167, v53
	v_fmac_f32_e32 v109, v167, v214
	v_fmac_f32_e32 v110, v183, v21
	v_fmac_f32_e32 v111, v183, v37
	v_fmac_f32_e32 v112, v183, v53
	v_fmac_f32_e32 v113, v183, v214
	v_fmac_f32_e32 v106, v168, v22
	v_fmac_f32_e32 v107, v168, v38
	v_fmac_f32_e32 v108, v168, v54
	v_fmac_f32_e32 v109, v168, v215
	v_fmac_f32_e32 v110, v184, v22
	v_fmac_f32_e32 v111, v184, v38
	v_fmac_f32_e32 v112, v184, v54
	v_fmac_f32_e32 v113, v184, v215
	v_fmac_f32_e32 v106, v169, v23
	v_fmac_f32_e32 v107, v169, v39
	v_fmac_f32_e32 v108, v169, v55
	v_fmac_f32_e32 v109, v169, v216
	v_fmac_f32_e32 v110, v185, v23
	v_fmac_f32_e32 v111, v185, v39
	v_fmac_f32_e32 v112, v185, v55
	v_fmac_f32_e32 v113, v185, v216
	v_fmac_f32_e32 v106, v170, v24
	v_fmac_f32_e32 v107, v170, v40
	v_fmac_f32_e32 v108, v170, v56
	v_fmac_f32_e32 v109, v170, v217
	v_fmac_f32_e32 v110, v186, v24
	v_fmac_f32_e32 v111, v186, v40
	v_fmac_f32_e32 v112, v186, v56
	v_fmac_f32_e32 v113, v186, v217
	v_fmac_f32_e32 v106, v171, v25
	v_fmac_f32_e32 v107, v171, v41
	v_fmac_f32_e32 v108, v171, v57
	v_fmac_f32_e32 v109, v171, v218
	v_fmac_f32_e32 v110, v187, v25
	v_fmac_f32_e32 v111, v187, v41
	v_fmac_f32_e32 v112, v187, v57
	v_fmac_f32_e32 v113, v187, v218
	v_fmac_f32_e32 v106, v172, v26
	v_fmac_f32_e32 v107, v172, v42
	v_fmac_f32_e32 v108, v172, v58
	v_fmac_f32_e32 v109, v172, v219
	v_fmac_f32_e32 v110, v188, v26
	v_fmac_f32_e32 v111, v188, v42
	v_fmac_f32_e32 v112, v188, v58
	v_fmac_f32_e32 v113, v188, v219
	v_fmac_f32_e32 v106, v173, v27
	v_fmac_f32_e32 v107, v173, v43
	v_fmac_f32_e32 v108, v173, v59
	v_fmac_f32_e32 v109, v173, v220
	v_fmac_f32_e32 v110, v189, v27
	v_fmac_f32_e32 v111, v189, v43
	v_fmac_f32_e32 v112, v189, v59
	v_fmac_f32_e32 v113, v189, v220
	v_fmac_f32_e32 v106, v174, v28
	v_fmac_f32_e32 v107, v174, v44
	v_fmac_f32_e32 v108, v174, v60
	v_fmac_f32_e32 v109, v174, v221
	v_fmac_f32_e32 v110, v190, v28
	v_fmac_f32_e32 v111, v190, v44
	v_fmac_f32_e32 v112, v190, v60
	v_fmac_f32_e32 v113, v190, v221
	v_fmac_f32_e32 v106, v175, v29
	v_fmac_f32_e32 v107, v175, v45
	v_fmac_f32_e32 v108, v175, v61
	v_fmac_f32_e32 v109, v175, v222
	v_fmac_f32_e32 v110, v191, v29
	v_fmac_f32_e32 v111, v191, v45
	v_fmac_f32_e32 v112, v191, v61
	v_fmac_f32_e32 v113, v191, v222
	v_fmac_f32_e32 v106, v176, v30
	v_fmac_f32_e32 v107, v176, v46
	v_fmac_f32_e32 v108, v176, v62
	v_fmac_f32_e32 v109, v176, v223
	v_fmac_f32_e32 v110, v192, v30
	v_fmac_f32_e32 v111, v192, v46
	v_fmac_f32_e32 v112, v192, v62
	v_fmac_f32_e32 v113, v192, v223
	v_fmac_f32_e32 v106, v177, v31
	v_fmac_f32_e32 v107, v177, v47
	v_fmac_f32_e32 v108, v177, v63
	v_fmac_f32_e32 v109, v177, v224
	v_fmac_f32_e32 v110, v193, v31
	v_fmac_f32_e32 v111, v193, v47
	v_fmac_f32_e32 v112, v193, v63
	v_fmac_f32_e32 v113, v193, v224
	global_load_dwordx4 v[162:165], v4, s[10:11]
	global_load_dwordx4 v[166:169], v4, s[10:11] offset:16
	global_load_dwordx4 v[170:173], v4, s[10:11] offset:32
	global_load_dwordx4 v[174:177], v4, s[10:11] offset:48
	s_add_u32 s10, s10, 0x9000
	s_addc_u32 s11, s11, 0
	global_load_dwordx4 v[178:181], v4, s[10:11]
	global_load_dwordx4 v[182:185], v4, s[10:11] offset:16
	global_load_dwordx4 v[186:189], v4, s[10:11] offset:32
	global_load_dwordx4 v[190:193], v4, s[10:11] offset:48
	s_add_u32 s10, s10, 0x9000
	s_addc_u32 s11, s11, 0
	s_waitcnt vmcnt(8)
	v_mul_f32_e32 v114, v194, v16
	v_mul_f32_e32 v115, v194, v32
	v_mul_f32_e32 v116, v194, v48
	v_mul_f32_e32 v117, v194, v64
	v_mul_f32_e32 v118, v226, v16
	v_mul_f32_e32 v119, v226, v32
	v_mul_f32_e32 v120, v226, v48
	v_mul_f32_e32 v121, v226, v64
	v_fmac_f32_e32 v114, v195, v17
	v_fmac_f32_e32 v115, v195, v33
	v_fmac_f32_e32 v116, v195, v49
	v_fmac_f32_e32 v117, v195, v65
	v_fmac_f32_e32 v118, v227, v17
	v_fmac_f32_e32 v119, v227, v33
	v_fmac_f32_e32 v120, v227, v49
	v_fmac_f32_e32 v121, v227, v65
	v_fmac_f32_e32 v114, v196, v18
	v_fmac_f32_e32 v115, v196, v34
	v_fmac_f32_e32 v116, v196, v50
	v_fmac_f32_e32 v117, v196, v211
	v_fmac_f32_e32 v118, v228, v18
	v_fmac_f32_e32 v119, v228, v34
	v_fmac_f32_e32 v120, v228, v50
	v_fmac_f32_e32 v121, v228, v211
	v_fmac_f32_e32 v114, v197, v19
	v_fmac_f32_e32 v115, v197, v35
	v_fmac_f32_e32 v116, v197, v51
	v_fmac_f32_e32 v117, v197, v212
	v_fmac_f32_e32 v118, v229, v19
	v_fmac_f32_e32 v119, v229, v35
	v_fmac_f32_e32 v120, v229, v51
	v_fmac_f32_e32 v121, v229, v212
	v_fmac_f32_e32 v114, v198, v20
	v_fmac_f32_e32 v115, v198, v36
	v_fmac_f32_e32 v116, v198, v52
	v_fmac_f32_e32 v117, v198, v213
	v_fmac_f32_e32 v118, v230, v20
	v_fmac_f32_e32 v119, v230, v36
	v_fmac_f32_e32 v120, v230, v52
	v_fmac_f32_e32 v121, v230, v213
	v_fmac_f32_e32 v114, v199, v21
	v_fmac_f32_e32 v115, v199, v37
	v_fmac_f32_e32 v116, v199, v53
	v_fmac_f32_e32 v117, v199, v214
	v_fmac_f32_e32 v118, v231, v21
	v_fmac_f32_e32 v119, v231, v37
	v_fmac_f32_e32 v120, v231, v53
	v_fmac_f32_e32 v121, v231, v214
	v_fmac_f32_e32 v114, v200, v22
	v_fmac_f32_e32 v115, v200, v38
	v_fmac_f32_e32 v116, v200, v54
	v_fmac_f32_e32 v117, v200, v215
	v_fmac_f32_e32 v118, v232, v22
	v_fmac_f32_e32 v119, v232, v38
	v_fmac_f32_e32 v120, v232, v54
	v_fmac_f32_e32 v121, v232, v215
	v_fmac_f32_e32 v114, v201, v23
	v_fmac_f32_e32 v115, v201, v39
	v_fmac_f32_e32 v116, v201, v55
	v_fmac_f32_e32 v117, v201, v216
	v_fmac_f32_e32 v118, v233, v23
	v_fmac_f32_e32 v119, v233, v39
	v_fmac_f32_e32 v120, v233, v55
	v_fmac_f32_e32 v121, v233, v216
	v_fmac_f32_e32 v114, v202, v24
	v_fmac_f32_e32 v115, v202, v40
	v_fmac_f32_e32 v116, v202, v56
	v_fmac_f32_e32 v117, v202, v217
	v_fmac_f32_e32 v118, v234, v24
	v_fmac_f32_e32 v119, v234, v40
	v_fmac_f32_e32 v120, v234, v56
	v_fmac_f32_e32 v121, v234, v217
	v_fmac_f32_e32 v114, v203, v25
	v_fmac_f32_e32 v115, v203, v41
	v_fmac_f32_e32 v116, v203, v57
	v_fmac_f32_e32 v117, v203, v218
	v_fmac_f32_e32 v118, v235, v25
	v_fmac_f32_e32 v119, v235, v41
	v_fmac_f32_e32 v120, v235, v57
	v_fmac_f32_e32 v121, v235, v218
	v_fmac_f32_e32 v114, v204, v26
	v_fmac_f32_e32 v115, v204, v42
	v_fmac_f32_e32 v116, v204, v58
	v_fmac_f32_e32 v117, v204, v219
	v_fmac_f32_e32 v118, v236, v26
	v_fmac_f32_e32 v119, v236, v42
	v_fmac_f32_e32 v120, v236, v58
	v_fmac_f32_e32 v121, v236, v219
	v_fmac_f32_e32 v114, v205, v27
	v_fmac_f32_e32 v115, v205, v43
	v_fmac_f32_e32 v116, v205, v59
	v_fmac_f32_e32 v117, v205, v220
	v_fmac_f32_e32 v118, v237, v27
	v_fmac_f32_e32 v119, v237, v43
	v_fmac_f32_e32 v120, v237, v59
	v_fmac_f32_e32 v121, v237, v220
	v_fmac_f32_e32 v114, v206, v28
	v_fmac_f32_e32 v115, v206, v44
	v_fmac_f32_e32 v116, v206, v60
	v_fmac_f32_e32 v117, v206, v221
	v_fmac_f32_e32 v118, v238, v28
	v_fmac_f32_e32 v119, v238, v44
	v_fmac_f32_e32 v120, v238, v60
	v_fmac_f32_e32 v121, v238, v221
	v_fmac_f32_e32 v114, v207, v29
	v_fmac_f32_e32 v115, v207, v45
	v_fmac_f32_e32 v116, v207, v61
	v_fmac_f32_e32 v117, v207, v222
	v_fmac_f32_e32 v118, v239, v29
	v_fmac_f32_e32 v119, v239, v45
	v_fmac_f32_e32 v120, v239, v61
	v_fmac_f32_e32 v121, v239, v222
	v_fmac_f32_e32 v114, v208, v30
	v_fmac_f32_e32 v115, v208, v46
	v_fmac_f32_e32 v116, v208, v62
	v_fmac_f32_e32 v117, v208, v223
	v_fmac_f32_e32 v118, v240, v30
	v_fmac_f32_e32 v119, v240, v46
	v_fmac_f32_e32 v120, v240, v62
	v_fmac_f32_e32 v121, v240, v223
	v_fmac_f32_e32 v114, v209, v31
	v_fmac_f32_e32 v115, v209, v47
	v_fmac_f32_e32 v116, v209, v63
	v_fmac_f32_e32 v117, v209, v224
	v_fmac_f32_e32 v118, v241, v31
	v_fmac_f32_e32 v119, v241, v47
	v_fmac_f32_e32 v120, v241, v63
	v_fmac_f32_e32 v121, v241, v224
	global_load_dwordx4 v[194:197], v4, s[10:11]
	global_load_dwordx4 v[198:201], v4, s[10:11] offset:16
	global_load_dwordx4 v[202:205], v4, s[10:11] offset:32
	global_load_dwordx4 v[206:209], v4, s[10:11] offset:48
	s_add_u32 s10, s10, 0x9000
	s_addc_u32 s11, s11, 0
	global_load_dwordx4 v[226:229], v4, s[10:11]
	global_load_dwordx4 v[230:233], v4, s[10:11] offset:16
	global_load_dwordx4 v[234:237], v4, s[10:11] offset:32
	global_load_dwordx4 v[238:241], v4, s[10:11] offset:48
	s_add_u32 s10, s10, 0x9000
	s_addc_u32 s11, s11, 0
	s_waitcnt vmcnt(8)
	v_mul_f32_e32 v122, v162, v16
	v_mul_f32_e32 v123, v162, v32
	v_mul_f32_e32 v124, v162, v48
	v_mul_f32_e32 v125, v162, v64
	v_mul_f32_e32 v126, v178, v16
	v_mul_f32_e32 v127, v178, v32
	v_mul_f32_e32 v128, v178, v48
	v_mul_f32_e32 v129, v178, v64
	v_fmac_f32_e32 v122, v163, v17
	v_fmac_f32_e32 v123, v163, v33
	v_fmac_f32_e32 v124, v163, v49
	v_fmac_f32_e32 v125, v163, v65
	v_fmac_f32_e32 v126, v179, v17
	v_fmac_f32_e32 v127, v179, v33
	v_fmac_f32_e32 v128, v179, v49
	v_fmac_f32_e32 v129, v179, v65
	v_fmac_f32_e32 v122, v164, v18
	v_fmac_f32_e32 v123, v164, v34
	v_fmac_f32_e32 v124, v164, v50
	v_fmac_f32_e32 v125, v164, v211
	v_fmac_f32_e32 v126, v180, v18
	v_fmac_f32_e32 v127, v180, v34
	v_fmac_f32_e32 v128, v180, v50
	v_fmac_f32_e32 v129, v180, v211
	v_fmac_f32_e32 v122, v165, v19
	v_fmac_f32_e32 v123, v165, v35
	v_fmac_f32_e32 v124, v165, v51
	v_fmac_f32_e32 v125, v165, v212
	v_fmac_f32_e32 v126, v181, v19
	v_fmac_f32_e32 v127, v181, v35
	v_fmac_f32_e32 v128, v181, v51
	v_fmac_f32_e32 v129, v181, v212
	v_fmac_f32_e32 v122, v166, v20
	v_fmac_f32_e32 v123, v166, v36
	v_fmac_f32_e32 v124, v166, v52
	v_fmac_f32_e32 v125, v166, v213
	v_fmac_f32_e32 v126, v182, v20
	v_fmac_f32_e32 v127, v182, v36
	v_fmac_f32_e32 v128, v182, v52
	v_fmac_f32_e32 v129, v182, v213
	v_fmac_f32_e32 v122, v167, v21
	v_fmac_f32_e32 v123, v167, v37
	v_fmac_f32_e32 v124, v167, v53
	v_fmac_f32_e32 v125, v167, v214
	v_fmac_f32_e32 v126, v183, v21
	v_fmac_f32_e32 v127, v183, v37
	v_fmac_f32_e32 v128, v183, v53
	v_fmac_f32_e32 v129, v183, v214
	v_fmac_f32_e32 v122, v168, v22
	v_fmac_f32_e32 v123, v168, v38
	v_fmac_f32_e32 v124, v168, v54
	v_fmac_f32_e32 v125, v168, v215
	v_fmac_f32_e32 v126, v184, v22
	v_fmac_f32_e32 v127, v184, v38
	v_fmac_f32_e32 v128, v184, v54
	v_fmac_f32_e32 v129, v184, v215
	v_fmac_f32_e32 v122, v169, v23
	v_fmac_f32_e32 v123, v169, v39
	v_fmac_f32_e32 v124, v169, v55
	v_fmac_f32_e32 v125, v169, v216
	v_fmac_f32_e32 v126, v185, v23
	v_fmac_f32_e32 v127, v185, v39
	v_fmac_f32_e32 v128, v185, v55
	v_fmac_f32_e32 v129, v185, v216
	v_fmac_f32_e32 v122, v170, v24
	v_fmac_f32_e32 v123, v170, v40
	v_fmac_f32_e32 v124, v170, v56
	v_fmac_f32_e32 v125, v170, v217
	v_fmac_f32_e32 v126, v186, v24
	v_fmac_f32_e32 v127, v186, v40
	v_fmac_f32_e32 v128, v186, v56
	v_fmac_f32_e32 v129, v186, v217
	v_fmac_f32_e32 v122, v171, v25
	v_fmac_f32_e32 v123, v171, v41
	v_fmac_f32_e32 v124, v171, v57
	v_fmac_f32_e32 v125, v171, v218
	v_fmac_f32_e32 v126, v187, v25
	v_fmac_f32_e32 v127, v187, v41
	v_fmac_f32_e32 v128, v187, v57
	v_fmac_f32_e32 v129, v187, v218
	v_fmac_f32_e32 v122, v172, v26
	v_fmac_f32_e32 v123, v172, v42
	v_fmac_f32_e32 v124, v172, v58
	v_fmac_f32_e32 v125, v172, v219
	v_fmac_f32_e32 v126, v188, v26
	v_fmac_f32_e32 v127, v188, v42
	v_fmac_f32_e32 v128, v188, v58
	v_fmac_f32_e32 v129, v188, v219
	v_fmac_f32_e32 v122, v173, v27
	v_fmac_f32_e32 v123, v173, v43
	v_fmac_f32_e32 v124, v173, v59
	v_fmac_f32_e32 v125, v173, v220
	v_fmac_f32_e32 v126, v189, v27
	v_fmac_f32_e32 v127, v189, v43
	v_fmac_f32_e32 v128, v189, v59
	v_fmac_f32_e32 v129, v189, v220
	v_fmac_f32_e32 v122, v174, v28
	v_fmac_f32_e32 v123, v174, v44
	v_fmac_f32_e32 v124, v174, v60
	v_fmac_f32_e32 v125, v174, v221
	v_fmac_f32_e32 v126, v190, v28
	v_fmac_f32_e32 v127, v190, v44
	v_fmac_f32_e32 v128, v190, v60
	v_fmac_f32_e32 v129, v190, v221
	v_fmac_f32_e32 v122, v175, v29
	v_fmac_f32_e32 v123, v175, v45
	v_fmac_f32_e32 v124, v175, v61
	v_fmac_f32_e32 v125, v175, v222
	v_fmac_f32_e32 v126, v191, v29
	v_fmac_f32_e32 v127, v191, v45
	v_fmac_f32_e32 v128, v191, v61
	v_fmac_f32_e32 v129, v191, v222
	v_fmac_f32_e32 v122, v176, v30
	v_fmac_f32_e32 v123, v176, v46
	v_fmac_f32_e32 v124, v176, v62
	v_fmac_f32_e32 v125, v176, v223
	v_fmac_f32_e32 v126, v192, v30
	v_fmac_f32_e32 v127, v192, v46
	v_fmac_f32_e32 v128, v192, v62
	v_fmac_f32_e32 v129, v192, v223
	v_fmac_f32_e32 v122, v177, v31
	v_fmac_f32_e32 v123, v177, v47
	v_fmac_f32_e32 v124, v177, v63
	v_fmac_f32_e32 v125, v177, v224
	v_fmac_f32_e32 v126, v193, v31
	v_fmac_f32_e32 v127, v193, v47
	v_fmac_f32_e32 v128, v193, v63
	v_fmac_f32_e32 v129, v193, v224
	global_load_dwordx4 v[162:165], v4, s[10:11]
	global_load_dwordx4 v[166:169], v4, s[10:11] offset:16
	global_load_dwordx4 v[170:173], v4, s[10:11] offset:32
	global_load_dwordx4 v[174:177], v4, s[10:11] offset:48
	s_add_u32 s10, s10, 0x9000
	s_addc_u32 s11, s11, 0
	global_load_dwordx4 v[178:181], v4, s[10:11]
	global_load_dwordx4 v[182:185], v4, s[10:11] offset:16
	global_load_dwordx4 v[186:189], v4, s[10:11] offset:32
	global_load_dwordx4 v[190:193], v4, s[10:11] offset:48
	s_add_u32 s10, s10, 0x9000
	s_addc_u32 s11, s11, 0
	s_waitcnt vmcnt(8)
	v_mul_f32_e32 v130, v194, v16
	v_mul_f32_e32 v131, v194, v32
	v_mul_f32_e32 v132, v194, v48
	v_mul_f32_e32 v133, v194, v64
	v_mul_f32_e32 v134, v226, v16
	v_mul_f32_e32 v135, v226, v32
	v_mul_f32_e32 v136, v226, v48
	v_mul_f32_e32 v137, v226, v64
	v_fmac_f32_e32 v130, v195, v17
	v_fmac_f32_e32 v131, v195, v33
	v_fmac_f32_e32 v132, v195, v49
	v_fmac_f32_e32 v133, v195, v65
	v_fmac_f32_e32 v134, v227, v17
	v_fmac_f32_e32 v135, v227, v33
	v_fmac_f32_e32 v136, v227, v49
	v_fmac_f32_e32 v137, v227, v65
	v_fmac_f32_e32 v130, v196, v18
	v_fmac_f32_e32 v131, v196, v34
	v_fmac_f32_e32 v132, v196, v50
	v_fmac_f32_e32 v133, v196, v211
	v_fmac_f32_e32 v134, v228, v18
	v_fmac_f32_e32 v135, v228, v34
	v_fmac_f32_e32 v136, v228, v50
	v_fmac_f32_e32 v137, v228, v211
	v_fmac_f32_e32 v130, v197, v19
	v_fmac_f32_e32 v131, v197, v35
	v_fmac_f32_e32 v132, v197, v51
	v_fmac_f32_e32 v133, v197, v212
	v_fmac_f32_e32 v134, v229, v19
	v_fmac_f32_e32 v135, v229, v35
	v_fmac_f32_e32 v136, v229, v51
	v_fmac_f32_e32 v137, v229, v212
	v_fmac_f32_e32 v130, v198, v20
	v_fmac_f32_e32 v131, v198, v36
	v_fmac_f32_e32 v132, v198, v52
	v_fmac_f32_e32 v133, v198, v213
	v_fmac_f32_e32 v134, v230, v20
	v_fmac_f32_e32 v135, v230, v36
	v_fmac_f32_e32 v136, v230, v52
	v_fmac_f32_e32 v137, v230, v213
	v_fmac_f32_e32 v130, v199, v21
	v_fmac_f32_e32 v131, v199, v37
	v_fmac_f32_e32 v132, v199, v53
	v_fmac_f32_e32 v133, v199, v214
	v_fmac_f32_e32 v134, v231, v21
	v_fmac_f32_e32 v135, v231, v37
	v_fmac_f32_e32 v136, v231, v53
	v_fmac_f32_e32 v137, v231, v214
	v_fmac_f32_e32 v130, v200, v22
	v_fmac_f32_e32 v131, v200, v38
	v_fmac_f32_e32 v132, v200, v54
	v_fmac_f32_e32 v133, v200, v215
	v_fmac_f32_e32 v134, v232, v22
	v_fmac_f32_e32 v135, v232, v38
	v_fmac_f32_e32 v136, v232, v54
	v_fmac_f32_e32 v137, v232, v215
	v_fmac_f32_e32 v130, v201, v23
	v_fmac_f32_e32 v131, v201, v39
	v_fmac_f32_e32 v132, v201, v55
	v_fmac_f32_e32 v133, v201, v216
	v_fmac_f32_e32 v134, v233, v23
	v_fmac_f32_e32 v135, v233, v39
	v_fmac_f32_e32 v136, v233, v55
	v_fmac_f32_e32 v137, v233, v216
	v_fmac_f32_e32 v130, v202, v24
	v_fmac_f32_e32 v131, v202, v40
	v_fmac_f32_e32 v132, v202, v56
	v_fmac_f32_e32 v133, v202, v217
	v_fmac_f32_e32 v134, v234, v24
	v_fmac_f32_e32 v135, v234, v40
	v_fmac_f32_e32 v136, v234, v56
	v_fmac_f32_e32 v137, v234, v217
	v_fmac_f32_e32 v130, v203, v25
	v_fmac_f32_e32 v131, v203, v41
	v_fmac_f32_e32 v132, v203, v57
	v_fmac_f32_e32 v133, v203, v218
	v_fmac_f32_e32 v134, v235, v25
	v_fmac_f32_e32 v135, v235, v41
	v_fmac_f32_e32 v136, v235, v57
	v_fmac_f32_e32 v137, v235, v218
	v_fmac_f32_e32 v130, v204, v26
	v_fmac_f32_e32 v131, v204, v42
	v_fmac_f32_e32 v132, v204, v58
	v_fmac_f32_e32 v133, v204, v219
	v_fmac_f32_e32 v134, v236, v26
	v_fmac_f32_e32 v135, v236, v42
	v_fmac_f32_e32 v136, v236, v58
	v_fmac_f32_e32 v137, v236, v219
	v_fmac_f32_e32 v130, v205, v27
	v_fmac_f32_e32 v131, v205, v43
	v_fmac_f32_e32 v132, v205, v59
	v_fmac_f32_e32 v133, v205, v220
	v_fmac_f32_e32 v134, v237, v27
	v_fmac_f32_e32 v135, v237, v43
	v_fmac_f32_e32 v136, v237, v59
	v_fmac_f32_e32 v137, v237, v220
	v_fmac_f32_e32 v130, v206, v28
	v_fmac_f32_e32 v131, v206, v44
	v_fmac_f32_e32 v132, v206, v60
	v_fmac_f32_e32 v133, v206, v221
	v_fmac_f32_e32 v134, v238, v28
	v_fmac_f32_e32 v135, v238, v44
	v_fmac_f32_e32 v136, v238, v60
	v_fmac_f32_e32 v137, v238, v221
	v_fmac_f32_e32 v130, v207, v29
	v_fmac_f32_e32 v131, v207, v45
	v_fmac_f32_e32 v132, v207, v61
	v_fmac_f32_e32 v133, v207, v222
	v_fmac_f32_e32 v134, v239, v29
	v_fmac_f32_e32 v135, v239, v45
	v_fmac_f32_e32 v136, v239, v61
	v_fmac_f32_e32 v137, v239, v222
	v_fmac_f32_e32 v130, v208, v30
	v_fmac_f32_e32 v131, v208, v46
	v_fmac_f32_e32 v132, v208, v62
	v_fmac_f32_e32 v133, v208, v223
	v_fmac_f32_e32 v134, v240, v30
	v_fmac_f32_e32 v135, v240, v46
	v_fmac_f32_e32 v136, v240, v62
	v_fmac_f32_e32 v137, v240, v223
	v_fmac_f32_e32 v130, v209, v31
	v_fmac_f32_e32 v131, v209, v47
	v_fmac_f32_e32 v132, v209, v63
	v_fmac_f32_e32 v133, v209, v224
	v_fmac_f32_e32 v134, v241, v31
	v_fmac_f32_e32 v135, v241, v47
	v_fmac_f32_e32 v136, v241, v63
	v_fmac_f32_e32 v137, v241, v224
	global_load_dwordx4 v[194:197], v4, s[10:11]
	global_load_dwordx4 v[198:201], v4, s[10:11] offset:16
	global_load_dwordx4 v[202:205], v4, s[10:11] offset:32
	global_load_dwordx4 v[206:209], v4, s[10:11] offset:48
	s_add_u32 s10, s10, 0x9000
	s_addc_u32 s11, s11, 0
	global_load_dwordx4 v[226:229], v4, s[10:11]
	global_load_dwordx4 v[230:233], v4, s[10:11] offset:16
	global_load_dwordx4 v[234:237], v4, s[10:11] offset:32
	global_load_dwordx4 v[238:241], v4, s[10:11] offset:48
	s_add_u32 s10, s10, 0x9000
	s_addc_u32 s11, s11, 0
	s_waitcnt vmcnt(8)
	v_mul_f32_e32 v138, v162, v16
	v_mul_f32_e32 v139, v162, v32
	v_mul_f32_e32 v140, v162, v48
	v_mul_f32_e32 v141, v162, v64
	v_mul_f32_e32 v142, v178, v16
	v_mul_f32_e32 v143, v178, v32
	v_mul_f32_e32 v144, v178, v48
	v_mul_f32_e32 v145, v178, v64
	v_fmac_f32_e32 v138, v163, v17
	v_fmac_f32_e32 v139, v163, v33
	v_fmac_f32_e32 v140, v163, v49
	v_fmac_f32_e32 v141, v163, v65
	v_fmac_f32_e32 v142, v179, v17
	v_fmac_f32_e32 v143, v179, v33
	v_fmac_f32_e32 v144, v179, v49
	v_fmac_f32_e32 v145, v179, v65
	v_fmac_f32_e32 v138, v164, v18
	v_fmac_f32_e32 v139, v164, v34
	v_fmac_f32_e32 v140, v164, v50
	v_fmac_f32_e32 v141, v164, v211
	v_fmac_f32_e32 v142, v180, v18
	v_fmac_f32_e32 v143, v180, v34
	v_fmac_f32_e32 v144, v180, v50
	v_fmac_f32_e32 v145, v180, v211
	v_fmac_f32_e32 v138, v165, v19
	v_fmac_f32_e32 v139, v165, v35
	v_fmac_f32_e32 v140, v165, v51
	v_fmac_f32_e32 v141, v165, v212
	v_fmac_f32_e32 v142, v181, v19
	v_fmac_f32_e32 v143, v181, v35
	v_fmac_f32_e32 v144, v181, v51
	v_fmac_f32_e32 v145, v181, v212
	v_fmac_f32_e32 v138, v166, v20
	v_fmac_f32_e32 v139, v166, v36
	v_fmac_f32_e32 v140, v166, v52
	v_fmac_f32_e32 v141, v166, v213
	v_fmac_f32_e32 v142, v182, v20
	v_fmac_f32_e32 v143, v182, v36
	v_fmac_f32_e32 v144, v182, v52
	v_fmac_f32_e32 v145, v182, v213
	v_fmac_f32_e32 v138, v167, v21
	v_fmac_f32_e32 v139, v167, v37
	v_fmac_f32_e32 v140, v167, v53
	v_fmac_f32_e32 v141, v167, v214
	v_fmac_f32_e32 v142, v183, v21
	v_fmac_f32_e32 v143, v183, v37
	v_fmac_f32_e32 v144, v183, v53
	v_fmac_f32_e32 v145, v183, v214
	v_fmac_f32_e32 v138, v168, v22
	v_fmac_f32_e32 v139, v168, v38
	v_fmac_f32_e32 v140, v168, v54
	v_fmac_f32_e32 v141, v168, v215
	v_fmac_f32_e32 v142, v184, v22
	v_fmac_f32_e32 v143, v184, v38
	v_fmac_f32_e32 v144, v184, v54
	v_fmac_f32_e32 v145, v184, v215
	v_fmac_f32_e32 v138, v169, v23
	v_fmac_f32_e32 v139, v169, v39
	v_fmac_f32_e32 v140, v169, v55
	v_fmac_f32_e32 v141, v169, v216
	v_fmac_f32_e32 v142, v185, v23
	v_fmac_f32_e32 v143, v185, v39
	v_fmac_f32_e32 v144, v185, v55
	v_fmac_f32_e32 v145, v185, v216
	v_fmac_f32_e32 v138, v170, v24
	v_fmac_f32_e32 v139, v170, v40
	v_fmac_f32_e32 v140, v170, v56
	v_fmac_f32_e32 v141, v170, v217
	v_fmac_f32_e32 v142, v186, v24
	v_fmac_f32_e32 v143, v186, v40
	v_fmac_f32_e32 v144, v186, v56
	v_fmac_f32_e32 v145, v186, v217
	v_fmac_f32_e32 v138, v171, v25
	v_fmac_f32_e32 v139, v171, v41
	v_fmac_f32_e32 v140, v171, v57
	v_fmac_f32_e32 v141, v171, v218
	v_fmac_f32_e32 v142, v187, v25
	v_fmac_f32_e32 v143, v187, v41
	v_fmac_f32_e32 v144, v187, v57
	v_fmac_f32_e32 v145, v187, v218
	v_fmac_f32_e32 v138, v172, v26
	v_fmac_f32_e32 v139, v172, v42
	v_fmac_f32_e32 v140, v172, v58
	v_fmac_f32_e32 v141, v172, v219
	v_fmac_f32_e32 v142, v188, v26
	v_fmac_f32_e32 v143, v188, v42
	v_fmac_f32_e32 v144, v188, v58
	v_fmac_f32_e32 v145, v188, v219
	v_fmac_f32_e32 v138, v173, v27
	v_fmac_f32_e32 v139, v173, v43
	v_fmac_f32_e32 v140, v173, v59
	v_fmac_f32_e32 v141, v173, v220
	v_fmac_f32_e32 v142, v189, v27
	v_fmac_f32_e32 v143, v189, v43
	v_fmac_f32_e32 v144, v189, v59
	v_fmac_f32_e32 v145, v189, v220
	v_fmac_f32_e32 v138, v174, v28
	v_fmac_f32_e32 v139, v174, v44
	v_fmac_f32_e32 v140, v174, v60
	v_fmac_f32_e32 v141, v174, v221
	v_fmac_f32_e32 v142, v190, v28
	v_fmac_f32_e32 v143, v190, v44
	v_fmac_f32_e32 v144, v190, v60
	v_fmac_f32_e32 v145, v190, v221
	v_fmac_f32_e32 v138, v175, v29
	v_fmac_f32_e32 v139, v175, v45
	v_fmac_f32_e32 v140, v175, v61
	v_fmac_f32_e32 v141, v175, v222
	v_fmac_f32_e32 v142, v191, v29
	v_fmac_f32_e32 v143, v191, v45
	v_fmac_f32_e32 v144, v191, v61
	v_fmac_f32_e32 v145, v191, v222
	v_fmac_f32_e32 v138, v176, v30
	v_fmac_f32_e32 v139, v176, v46
	v_fmac_f32_e32 v140, v176, v62
	v_fmac_f32_e32 v141, v176, v223
	v_fmac_f32_e32 v142, v192, v30
	v_fmac_f32_e32 v143, v192, v46
	v_fmac_f32_e32 v144, v192, v62
	v_fmac_f32_e32 v145, v192, v223
	v_fmac_f32_e32 v138, v177, v31
	v_fmac_f32_e32 v139, v177, v47
	v_fmac_f32_e32 v140, v177, v63
	v_fmac_f32_e32 v141, v177, v224
	v_fmac_f32_e32 v142, v193, v31
	v_fmac_f32_e32 v143, v193, v47
	v_fmac_f32_e32 v144, v193, v63
	v_fmac_f32_e32 v145, v193, v224
	global_load_dwordx4 v[162:165], v4, s[10:11]
	global_load_dwordx4 v[166:169], v4, s[10:11] offset:16
	global_load_dwordx4 v[170:173], v4, s[10:11] offset:32
	global_load_dwordx4 v[174:177], v4, s[10:11] offset:48
	s_add_u32 s10, s10, 0x9000
	s_addc_u32 s11, s11, 0
	global_load_dwordx4 v[178:181], v4, s[10:11]
	global_load_dwordx4 v[182:185], v4, s[10:11] offset:16
	global_load_dwordx4 v[186:189], v4, s[10:11] offset:32
	global_load_dwordx4 v[190:193], v4, s[10:11] offset:48
	s_add_u32 s10, s10, 0x9000
	s_addc_u32 s11, s11, 0
	s_waitcnt vmcnt(8)
	v_mul_f32_e32 v146, v194, v16
	v_mul_f32_e32 v147, v194, v32
	v_mul_f32_e32 v148, v194, v48
	v_mul_f32_e32 v149, v194, v64
	v_mul_f32_e32 v150, v226, v16
	v_mul_f32_e32 v151, v226, v32
	v_mul_f32_e32 v152, v226, v48
	v_mul_f32_e32 v153, v226, v64
	v_fmac_f32_e32 v146, v195, v17
	v_fmac_f32_e32 v147, v195, v33
	v_fmac_f32_e32 v148, v195, v49
	v_fmac_f32_e32 v149, v195, v65
	v_fmac_f32_e32 v150, v227, v17
	v_fmac_f32_e32 v151, v227, v33
	v_fmac_f32_e32 v152, v227, v49
	v_fmac_f32_e32 v153, v227, v65
	v_fmac_f32_e32 v146, v196, v18
	v_fmac_f32_e32 v147, v196, v34
	v_fmac_f32_e32 v148, v196, v50
	v_fmac_f32_e32 v149, v196, v211
	v_fmac_f32_e32 v150, v228, v18
	v_fmac_f32_e32 v151, v228, v34
	v_fmac_f32_e32 v152, v228, v50
	v_fmac_f32_e32 v153, v228, v211
	v_fmac_f32_e32 v146, v197, v19
	v_fmac_f32_e32 v147, v197, v35
	v_fmac_f32_e32 v148, v197, v51
	v_fmac_f32_e32 v149, v197, v212
	v_fmac_f32_e32 v150, v229, v19
	v_fmac_f32_e32 v151, v229, v35
	v_fmac_f32_e32 v152, v229, v51
	v_fmac_f32_e32 v153, v229, v212
	v_fmac_f32_e32 v146, v198, v20
	v_fmac_f32_e32 v147, v198, v36
	v_fmac_f32_e32 v148, v198, v52
	v_fmac_f32_e32 v149, v198, v213
	v_fmac_f32_e32 v150, v230, v20
	v_fmac_f32_e32 v151, v230, v36
	v_fmac_f32_e32 v152, v230, v52
	v_fmac_f32_e32 v153, v230, v213
	v_fmac_f32_e32 v146, v199, v21
	v_fmac_f32_e32 v147, v199, v37
	v_fmac_f32_e32 v148, v199, v53
	v_fmac_f32_e32 v149, v199, v214
	v_fmac_f32_e32 v150, v231, v21
	v_fmac_f32_e32 v151, v231, v37
	v_fmac_f32_e32 v152, v231, v53
	v_fmac_f32_e32 v153, v231, v214
	v_fmac_f32_e32 v146, v200, v22
	v_fmac_f32_e32 v147, v200, v38
	v_fmac_f32_e32 v148, v200, v54
	v_fmac_f32_e32 v149, v200, v215
	v_fmac_f32_e32 v150, v232, v22
	v_fmac_f32_e32 v151, v232, v38
	v_fmac_f32_e32 v152, v232, v54
	v_fmac_f32_e32 v153, v232, v215
	v_fmac_f32_e32 v146, v201, v23
	v_fmac_f32_e32 v147, v201, v39
	v_fmac_f32_e32 v148, v201, v55
	v_fmac_f32_e32 v149, v201, v216
	v_fmac_f32_e32 v150, v233, v23
	v_fmac_f32_e32 v151, v233, v39
	v_fmac_f32_e32 v152, v233, v55
	v_fmac_f32_e32 v153, v233, v216
	v_fmac_f32_e32 v146, v202, v24
	v_fmac_f32_e32 v147, v202, v40
	v_fmac_f32_e32 v148, v202, v56
	v_fmac_f32_e32 v149, v202, v217
	v_fmac_f32_e32 v150, v234, v24
	v_fmac_f32_e32 v151, v234, v40
	v_fmac_f32_e32 v152, v234, v56
	v_fmac_f32_e32 v153, v234, v217
	v_fmac_f32_e32 v146, v203, v25
	v_fmac_f32_e32 v147, v203, v41
	v_fmac_f32_e32 v148, v203, v57
	v_fmac_f32_e32 v149, v203, v218
	v_fmac_f32_e32 v150, v235, v25
	v_fmac_f32_e32 v151, v235, v41
	v_fmac_f32_e32 v152, v235, v57
	v_fmac_f32_e32 v153, v235, v218
	v_fmac_f32_e32 v146, v204, v26
	v_fmac_f32_e32 v147, v204, v42
	v_fmac_f32_e32 v148, v204, v58
	v_fmac_f32_e32 v149, v204, v219
	v_fmac_f32_e32 v150, v236, v26
	v_fmac_f32_e32 v151, v236, v42
	v_fmac_f32_e32 v152, v236, v58
	v_fmac_f32_e32 v153, v236, v219
	v_fmac_f32_e32 v146, v205, v27
	v_fmac_f32_e32 v147, v205, v43
	v_fmac_f32_e32 v148, v205, v59
	v_fmac_f32_e32 v149, v205, v220
	v_fmac_f32_e32 v150, v237, v27
	v_fmac_f32_e32 v151, v237, v43
	v_fmac_f32_e32 v152, v237, v59
	v_fmac_f32_e32 v153, v237, v220
	v_fmac_f32_e32 v146, v206, v28
	v_fmac_f32_e32 v147, v206, v44
	v_fmac_f32_e32 v148, v206, v60
	v_fmac_f32_e32 v149, v206, v221
	v_fmac_f32_e32 v150, v238, v28
	v_fmac_f32_e32 v151, v238, v44
	v_fmac_f32_e32 v152, v238, v60
	v_fmac_f32_e32 v153, v238, v221
	v_fmac_f32_e32 v146, v207, v29
	v_fmac_f32_e32 v147, v207, v45
	v_fmac_f32_e32 v148, v207, v61
	v_fmac_f32_e32 v149, v207, v222
	v_fmac_f32_e32 v150, v239, v29
	v_fmac_f32_e32 v151, v239, v45
	v_fmac_f32_e32 v152, v239, v61
	v_fmac_f32_e32 v153, v239, v222
	v_fmac_f32_e32 v146, v208, v30
	v_fmac_f32_e32 v147, v208, v46
	v_fmac_f32_e32 v148, v208, v62
	v_fmac_f32_e32 v149, v208, v223
	v_fmac_f32_e32 v150, v240, v30
	v_fmac_f32_e32 v151, v240, v46
	v_fmac_f32_e32 v152, v240, v62
	v_fmac_f32_e32 v153, v240, v223
	v_fmac_f32_e32 v146, v209, v31
	v_fmac_f32_e32 v147, v209, v47
	v_fmac_f32_e32 v148, v209, v63
	v_fmac_f32_e32 v149, v209, v224
	v_fmac_f32_e32 v150, v241, v31
	v_fmac_f32_e32 v151, v241, v47
	v_fmac_f32_e32 v152, v241, v63
	v_fmac_f32_e32 v153, v241, v224
	s_waitcnt vmcnt(0)
	v_mul_f32_e32 v154, v162, v16
	v_mul_f32_e32 v155, v162, v32
	v_mul_f32_e32 v156, v162, v48
	v_mul_f32_e32 v157, v162, v64
	v_mul_f32_e32 v158, v178, v16
	v_mul_f32_e32 v159, v178, v32
	v_mul_f32_e32 v160, v178, v48
	v_mul_f32_e32 v161, v178, v64
	v_fmac_f32_e32 v154, v163, v17
	v_fmac_f32_e32 v155, v163, v33
	v_fmac_f32_e32 v156, v163, v49
	v_fmac_f32_e32 v157, v163, v65
	v_fmac_f32_e32 v158, v179, v17
	v_fmac_f32_e32 v159, v179, v33
	v_fmac_f32_e32 v160, v179, v49
	v_fmac_f32_e32 v161, v179, v65
	v_fmac_f32_e32 v154, v164, v18
	v_fmac_f32_e32 v155, v164, v34
	v_fmac_f32_e32 v156, v164, v50
	v_fmac_f32_e32 v157, v164, v211
	v_fmac_f32_e32 v158, v180, v18
	v_fmac_f32_e32 v159, v180, v34
	v_fmac_f32_e32 v160, v180, v50
	v_fmac_f32_e32 v161, v180, v211
	v_fmac_f32_e32 v154, v165, v19
	v_fmac_f32_e32 v155, v165, v35
	v_fmac_f32_e32 v156, v165, v51
	v_fmac_f32_e32 v157, v165, v212
	v_fmac_f32_e32 v158, v181, v19
	v_fmac_f32_e32 v159, v181, v35
	v_fmac_f32_e32 v160, v181, v51
	v_fmac_f32_e32 v161, v181, v212
	v_fmac_f32_e32 v154, v166, v20
	v_fmac_f32_e32 v155, v166, v36
	v_fmac_f32_e32 v156, v166, v52
	v_fmac_f32_e32 v157, v166, v213
	v_fmac_f32_e32 v158, v182, v20
	v_fmac_f32_e32 v159, v182, v36
	v_fmac_f32_e32 v160, v182, v52
	v_fmac_f32_e32 v161, v182, v213
	v_fmac_f32_e32 v154, v167, v21
	v_fmac_f32_e32 v155, v167, v37
	v_fmac_f32_e32 v156, v167, v53
	v_fmac_f32_e32 v157, v167, v214
	v_fmac_f32_e32 v158, v183, v21
	v_fmac_f32_e32 v159, v183, v37
	v_fmac_f32_e32 v160, v183, v53
	v_fmac_f32_e32 v161, v183, v214
	v_fmac_f32_e32 v154, v168, v22
	v_fmac_f32_e32 v155, v168, v38
	v_fmac_f32_e32 v156, v168, v54
	v_fmac_f32_e32 v157, v168, v215
	v_fmac_f32_e32 v158, v184, v22
	v_fmac_f32_e32 v159, v184, v38
	v_fmac_f32_e32 v160, v184, v54
	v_fmac_f32_e32 v161, v184, v215
	v_fmac_f32_e32 v154, v169, v23
	v_fmac_f32_e32 v155, v169, v39
	v_fmac_f32_e32 v156, v169, v55
	v_fmac_f32_e32 v157, v169, v216
	v_fmac_f32_e32 v158, v185, v23
	v_fmac_f32_e32 v159, v185, v39
	v_fmac_f32_e32 v160, v185, v55
	v_fmac_f32_e32 v161, v185, v216
	v_fmac_f32_e32 v154, v170, v24
	v_fmac_f32_e32 v155, v170, v40
	v_fmac_f32_e32 v156, v170, v56
	v_fmac_f32_e32 v157, v170, v217
	v_fmac_f32_e32 v158, v186, v24
	v_fmac_f32_e32 v159, v186, v40
	v_fmac_f32_e32 v160, v186, v56
	v_fmac_f32_e32 v161, v186, v217
	v_fmac_f32_e32 v154, v171, v25
	v_fmac_f32_e32 v155, v171, v41
	v_fmac_f32_e32 v156, v171, v57
	v_fmac_f32_e32 v157, v171, v218
	v_fmac_f32_e32 v158, v187, v25
	v_fmac_f32_e32 v159, v187, v41
	v_fmac_f32_e32 v160, v187, v57
	v_fmac_f32_e32 v161, v187, v218
	v_fmac_f32_e32 v154, v172, v26
	v_fmac_f32_e32 v155, v172, v42
	v_fmac_f32_e32 v156, v172, v58
	v_fmac_f32_e32 v157, v172, v219
	v_fmac_f32_e32 v158, v188, v26
	v_fmac_f32_e32 v159, v188, v42
	v_fmac_f32_e32 v160, v188, v58
	v_fmac_f32_e32 v161, v188, v219
	v_fmac_f32_e32 v154, v173, v27
	v_fmac_f32_e32 v155, v173, v43
	v_fmac_f32_e32 v156, v173, v59
	v_fmac_f32_e32 v157, v173, v220
	v_fmac_f32_e32 v158, v189, v27
	v_fmac_f32_e32 v159, v189, v43
	v_fmac_f32_e32 v160, v189, v59
	v_fmac_f32_e32 v161, v189, v220
	v_fmac_f32_e32 v154, v174, v28
	v_fmac_f32_e32 v155, v174, v44
	v_fmac_f32_e32 v156, v174, v60
	v_fmac_f32_e32 v157, v174, v221
	v_fmac_f32_e32 v158, v190, v28
	v_fmac_f32_e32 v159, v190, v44
	v_fmac_f32_e32 v160, v190, v60
	v_fmac_f32_e32 v161, v190, v221
	v_fmac_f32_e32 v154, v175, v29
	v_fmac_f32_e32 v155, v175, v45
	v_fmac_f32_e32 v156, v175, v61
	v_fmac_f32_e32 v157, v175, v222
	v_fmac_f32_e32 v158, v191, v29
	v_fmac_f32_e32 v159, v191, v45
	v_fmac_f32_e32 v160, v191, v61
	v_fmac_f32_e32 v161, v191, v222
	v_fmac_f32_e32 v154, v176, v30
	v_fmac_f32_e32 v155, v176, v46
	v_fmac_f32_e32 v156, v176, v62
	v_fmac_f32_e32 v157, v176, v223
	v_fmac_f32_e32 v158, v192, v30
	v_fmac_f32_e32 v159, v192, v46
	v_fmac_f32_e32 v160, v192, v62
	v_fmac_f32_e32 v161, v192, v223
	v_fmac_f32_e32 v154, v177, v31
	v_fmac_f32_e32 v155, v177, v47
	v_fmac_f32_e32 v156, v177, v63
	v_fmac_f32_e32 v157, v177, v224
	v_fmac_f32_e32 v158, v193, v31
	v_fmac_f32_e32 v159, v193, v47
	v_fmac_f32_e32 v160, v193, v63
	v_fmac_f32_e32 v161, v193, v224
	v_add_f32_dpp v98, v98, v98 quad_perm:[1,0,3,2] row_mask:0xf bank_mask:0xf
	v_add_f32_dpp v99, v99, v99 quad_perm:[1,0,3,2] row_mask:0xf bank_mask:0xf
	v_add_f32_dpp v100, v100, v100 quad_perm:[1,0,3,2] row_mask:0xf bank_mask:0xf
	v_add_f32_dpp v101, v101, v101 quad_perm:[1,0,3,2] row_mask:0xf bank_mask:0xf
	v_add_f32_dpp v102, v102, v102 quad_perm:[1,0,3,2] row_mask:0xf bank_mask:0xf
	v_add_f32_dpp v103, v103, v103 quad_perm:[1,0,3,2] row_mask:0xf bank_mask:0xf
	v_add_f32_dpp v104, v104, v104 quad_perm:[1,0,3,2] row_mask:0xf bank_mask:0xf
	v_add_f32_dpp v105, v105, v105 quad_perm:[1,0,3,2] row_mask:0xf bank_mask:0xf
	v_add_f32_dpp v106, v106, v106 quad_perm:[1,0,3,2] row_mask:0xf bank_mask:0xf
	v_add_f32_dpp v107, v107, v107 quad_perm:[1,0,3,2] row_mask:0xf bank_mask:0xf
	v_add_f32_dpp v108, v108, v108 quad_perm:[1,0,3,2] row_mask:0xf bank_mask:0xf
	v_add_f32_dpp v109, v109, v109 quad_perm:[1,0,3,2] row_mask:0xf bank_mask:0xf
	v_add_f32_dpp v110, v110, v110 quad_perm:[1,0,3,2] row_mask:0xf bank_mask:0xf
	v_add_f32_dpp v111, v111, v111 quad_perm:[1,0,3,2] row_mask:0xf bank_mask:0xf
	v_add_f32_dpp v112, v112, v112 quad_perm:[1,0,3,2] row_mask:0xf bank_mask:0xf
	v_add_f32_dpp v113, v113, v113 quad_perm:[1,0,3,2] row_mask:0xf bank_mask:0xf
	v_add_f32_dpp v114, v114, v114 quad_perm:[1,0,3,2] row_mask:0xf bank_mask:0xf
	v_add_f32_dpp v115, v115, v115 quad_perm:[1,0,3,2] row_mask:0xf bank_mask:0xf
	v_add_f32_dpp v116, v116, v116 quad_perm:[1,0,3,2] row_mask:0xf bank_mask:0xf
	v_add_f32_dpp v117, v117, v117 quad_perm:[1,0,3,2] row_mask:0xf bank_mask:0xf
	v_add_f32_dpp v118, v118, v118 quad_perm:[1,0,3,2] row_mask:0xf bank_mask:0xf
	v_add_f32_dpp v119, v119, v119 quad_perm:[1,0,3,2] row_mask:0xf bank_mask:0xf
	v_add_f32_dpp v120, v120, v120 quad_perm:[1,0,3,2] row_mask:0xf bank_mask:0xf
	v_add_f32_dpp v121, v121, v121 quad_perm:[1,0,3,2] row_mask:0xf bank_mask:0xf
	v_add_f32_dpp v122, v122, v122 quad_perm:[1,0,3,2] row_mask:0xf bank_mask:0xf
	v_add_f32_dpp v123, v123, v123 quad_perm:[1,0,3,2] row_mask:0xf bank_mask:0xf
	v_add_f32_dpp v124, v124, v124 quad_perm:[1,0,3,2] row_mask:0xf bank_mask:0xf
	v_add_f32_dpp v125, v125, v125 quad_perm:[1,0,3,2] row_mask:0xf bank_mask:0xf
	v_add_f32_dpp v126, v126, v126 quad_perm:[1,0,3,2] row_mask:0xf bank_mask:0xf
	v_add_f32_dpp v127, v127, v127 quad_perm:[1,0,3,2] row_mask:0xf bank_mask:0xf
	v_add_f32_dpp v128, v128, v128 quad_perm:[1,0,3,2] row_mask:0xf bank_mask:0xf
	v_add_f32_dpp v129, v129, v129 quad_perm:[1,0,3,2] row_mask:0xf bank_mask:0xf
	v_add_f32_dpp v130, v130, v130 quad_perm:[1,0,3,2] row_mask:0xf bank_mask:0xf
	v_add_f32_dpp v131, v131, v131 quad_perm:[1,0,3,2] row_mask:0xf bank_mask:0xf
	v_add_f32_dpp v132, v132, v132 quad_perm:[1,0,3,2] row_mask:0xf bank_mask:0xf
	v_add_f32_dpp v133, v133, v133 quad_perm:[1,0,3,2] row_mask:0xf bank_mask:0xf
	v_add_f32_dpp v134, v134, v134 quad_perm:[1,0,3,2] row_mask:0xf bank_mask:0xf
	v_add_f32_dpp v135, v135, v135 quad_perm:[1,0,3,2] row_mask:0xf bank_mask:0xf
	v_add_f32_dpp v136, v136, v136 quad_perm:[1,0,3,2] row_mask:0xf bank_mask:0xf
	v_add_f32_dpp v137, v137, v137 quad_perm:[1,0,3,2] row_mask:0xf bank_mask:0xf
	v_add_f32_dpp v138, v138, v138 quad_perm:[1,0,3,2] row_mask:0xf bank_mask:0xf
	v_add_f32_dpp v139, v139, v139 quad_perm:[1,0,3,2] row_mask:0xf bank_mask:0xf
	v_add_f32_dpp v140, v140, v140 quad_perm:[1,0,3,2] row_mask:0xf bank_mask:0xf
	v_add_f32_dpp v141, v141, v141 quad_perm:[1,0,3,2] row_mask:0xf bank_mask:0xf
	v_add_f32_dpp v142, v142, v142 quad_perm:[1,0,3,2] row_mask:0xf bank_mask:0xf
	v_add_f32_dpp v143, v143, v143 quad_perm:[1,0,3,2] row_mask:0xf bank_mask:0xf
	v_add_f32_dpp v144, v144, v144 quad_perm:[1,0,3,2] row_mask:0xf bank_mask:0xf
	v_add_f32_dpp v145, v145, v145 quad_perm:[1,0,3,2] row_mask:0xf bank_mask:0xf
	v_add_f32_dpp v146, v146, v146 quad_perm:[1,0,3,2] row_mask:0xf bank_mask:0xf
	v_add_f32_dpp v147, v147, v147 quad_perm:[1,0,3,2] row_mask:0xf bank_mask:0xf
	v_add_f32_dpp v148, v148, v148 quad_perm:[1,0,3,2] row_mask:0xf bank_mask:0xf
	v_add_f32_dpp v149, v149, v149 quad_perm:[1,0,3,2] row_mask:0xf bank_mask:0xf
	v_add_f32_dpp v150, v150, v150 quad_perm:[1,0,3,2] row_mask:0xf bank_mask:0xf
	v_add_f32_dpp v151, v151, v151 quad_perm:[1,0,3,2] row_mask:0xf bank_mask:0xf
	v_add_f32_dpp v152, v152, v152 quad_perm:[1,0,3,2] row_mask:0xf bank_mask:0xf
	v_add_f32_dpp v153, v153, v153 quad_perm:[1,0,3,2] row_mask:0xf bank_mask:0xf
	v_add_f32_dpp v154, v154, v154 quad_perm:[1,0,3,2] row_mask:0xf bank_mask:0xf
	v_add_f32_dpp v155, v155, v155 quad_perm:[1,0,3,2] row_mask:0xf bank_mask:0xf
	v_add_f32_dpp v156, v156, v156 quad_perm:[1,0,3,2] row_mask:0xf bank_mask:0xf
	v_add_f32_dpp v157, v157, v157 quad_perm:[1,0,3,2] row_mask:0xf bank_mask:0xf
	v_add_f32_dpp v158, v158, v158 quad_perm:[1,0,3,2] row_mask:0xf bank_mask:0xf
	v_add_f32_dpp v159, v159, v159 quad_perm:[1,0,3,2] row_mask:0xf bank_mask:0xf
	v_add_f32_dpp v160, v160, v160 quad_perm:[1,0,3,2] row_mask:0xf bank_mask:0xf
	v_add_f32_dpp v161, v161, v161 quad_perm:[1,0,3,2] row_mask:0xf bank_mask:0xf
	v_add_f32_dpp v98, v98, v98 quad_perm:[2,3,0,1] row_mask:0xf bank_mask:0xf
	v_add_f32_dpp v99, v99, v99 quad_perm:[2,3,0,1] row_mask:0xf bank_mask:0xf
	v_add_f32_dpp v100, v100, v100 quad_perm:[2,3,0,1] row_mask:0xf bank_mask:0xf
	v_add_f32_dpp v101, v101, v101 quad_perm:[2,3,0,1] row_mask:0xf bank_mask:0xf
	v_add_f32_dpp v102, v102, v102 quad_perm:[2,3,0,1] row_mask:0xf bank_mask:0xf
	v_add_f32_dpp v103, v103, v103 quad_perm:[2,3,0,1] row_mask:0xf bank_mask:0xf
	v_add_f32_dpp v104, v104, v104 quad_perm:[2,3,0,1] row_mask:0xf bank_mask:0xf
	v_add_f32_dpp v105, v105, v105 quad_perm:[2,3,0,1] row_mask:0xf bank_mask:0xf
	v_add_f32_dpp v106, v106, v106 quad_perm:[2,3,0,1] row_mask:0xf bank_mask:0xf
	v_add_f32_dpp v107, v107, v107 quad_perm:[2,3,0,1] row_mask:0xf bank_mask:0xf
	v_add_f32_dpp v108, v108, v108 quad_perm:[2,3,0,1] row_mask:0xf bank_mask:0xf
	v_add_f32_dpp v109, v109, v109 quad_perm:[2,3,0,1] row_mask:0xf bank_mask:0xf
	v_add_f32_dpp v110, v110, v110 quad_perm:[2,3,0,1] row_mask:0xf bank_mask:0xf
	v_add_f32_dpp v111, v111, v111 quad_perm:[2,3,0,1] row_mask:0xf bank_mask:0xf
	v_add_f32_dpp v112, v112, v112 quad_perm:[2,3,0,1] row_mask:0xf bank_mask:0xf
	v_add_f32_dpp v113, v113, v113 quad_perm:[2,3,0,1] row_mask:0xf bank_mask:0xf
	v_add_f32_dpp v114, v114, v114 quad_perm:[2,3,0,1] row_mask:0xf bank_mask:0xf
	v_add_f32_dpp v115, v115, v115 quad_perm:[2,3,0,1] row_mask:0xf bank_mask:0xf
	v_add_f32_dpp v116, v116, v116 quad_perm:[2,3,0,1] row_mask:0xf bank_mask:0xf
	v_add_f32_dpp v117, v117, v117 quad_perm:[2,3,0,1] row_mask:0xf bank_mask:0xf
	v_add_f32_dpp v118, v118, v118 quad_perm:[2,3,0,1] row_mask:0xf bank_mask:0xf
	v_add_f32_dpp v119, v119, v119 quad_perm:[2,3,0,1] row_mask:0xf bank_mask:0xf
	v_add_f32_dpp v120, v120, v120 quad_perm:[2,3,0,1] row_mask:0xf bank_mask:0xf
	v_add_f32_dpp v121, v121, v121 quad_perm:[2,3,0,1] row_mask:0xf bank_mask:0xf
	v_add_f32_dpp v122, v122, v122 quad_perm:[2,3,0,1] row_mask:0xf bank_mask:0xf
	v_add_f32_dpp v123, v123, v123 quad_perm:[2,3,0,1] row_mask:0xf bank_mask:0xf
	v_add_f32_dpp v124, v124, v124 quad_perm:[2,3,0,1] row_mask:0xf bank_mask:0xf
	v_add_f32_dpp v125, v125, v125 quad_perm:[2,3,0,1] row_mask:0xf bank_mask:0xf
	v_add_f32_dpp v126, v126, v126 quad_perm:[2,3,0,1] row_mask:0xf bank_mask:0xf
	v_add_f32_dpp v127, v127, v127 quad_perm:[2,3,0,1] row_mask:0xf bank_mask:0xf
	v_add_f32_dpp v128, v128, v128 quad_perm:[2,3,0,1] row_mask:0xf bank_mask:0xf
	v_add_f32_dpp v129, v129, v129 quad_perm:[2,3,0,1] row_mask:0xf bank_mask:0xf
	v_add_f32_dpp v130, v130, v130 quad_perm:[2,3,0,1] row_mask:0xf bank_mask:0xf
	v_add_f32_dpp v131, v131, v131 quad_perm:[2,3,0,1] row_mask:0xf bank_mask:0xf
	v_add_f32_dpp v132, v132, v132 quad_perm:[2,3,0,1] row_mask:0xf bank_mask:0xf
	v_add_f32_dpp v133, v133, v133 quad_perm:[2,3,0,1] row_mask:0xf bank_mask:0xf
	v_add_f32_dpp v134, v134, v134 quad_perm:[2,3,0,1] row_mask:0xf bank_mask:0xf
	v_add_f32_dpp v135, v135, v135 quad_perm:[2,3,0,1] row_mask:0xf bank_mask:0xf
	v_add_f32_dpp v136, v136, v136 quad_perm:[2,3,0,1] row_mask:0xf bank_mask:0xf
	v_add_f32_dpp v137, v137, v137 quad_perm:[2,3,0,1] row_mask:0xf bank_mask:0xf
	v_add_f32_dpp v138, v138, v138 quad_perm:[2,3,0,1] row_mask:0xf bank_mask:0xf
	v_add_f32_dpp v139, v139, v139 quad_perm:[2,3,0,1] row_mask:0xf bank_mask:0xf
	v_add_f32_dpp v140, v140, v140 quad_perm:[2,3,0,1] row_mask:0xf bank_mask:0xf
	v_add_f32_dpp v141, v141, v141 quad_perm:[2,3,0,1] row_mask:0xf bank_mask:0xf
	v_add_f32_dpp v142, v142, v142 quad_perm:[2,3,0,1] row_mask:0xf bank_mask:0xf
	v_add_f32_dpp v143, v143, v143 quad_perm:[2,3,0,1] row_mask:0xf bank_mask:0xf
	v_add_f32_dpp v144, v144, v144 quad_perm:[2,3,0,1] row_mask:0xf bank_mask:0xf
	v_add_f32_dpp v145, v145, v145 quad_perm:[2,3,0,1] row_mask:0xf bank_mask:0xf
	v_add_f32_dpp v146, v146, v146 quad_perm:[2,3,0,1] row_mask:0xf bank_mask:0xf
	v_add_f32_dpp v147, v147, v147 quad_perm:[2,3,0,1] row_mask:0xf bank_mask:0xf
	v_add_f32_dpp v148, v148, v148 quad_perm:[2,3,0,1] row_mask:0xf bank_mask:0xf
	v_add_f32_dpp v149, v149, v149 quad_perm:[2,3,0,1] row_mask:0xf bank_mask:0xf
	v_add_f32_dpp v150, v150, v150 quad_perm:[2,3,0,1] row_mask:0xf bank_mask:0xf
	v_add_f32_dpp v151, v151, v151 quad_perm:[2,3,0,1] row_mask:0xf bank_mask:0xf
	v_add_f32_dpp v152, v152, v152 quad_perm:[2,3,0,1] row_mask:0xf bank_mask:0xf
	v_add_f32_dpp v153, v153, v153 quad_perm:[2,3,0,1] row_mask:0xf bank_mask:0xf
	v_add_f32_dpp v154, v154, v154 quad_perm:[2,3,0,1] row_mask:0xf bank_mask:0xf
	v_add_f32_dpp v155, v155, v155 quad_perm:[2,3,0,1] row_mask:0xf bank_mask:0xf
	v_add_f32_dpp v156, v156, v156 quad_perm:[2,3,0,1] row_mask:0xf bank_mask:0xf
	v_add_f32_dpp v157, v157, v157 quad_perm:[2,3,0,1] row_mask:0xf bank_mask:0xf
	v_add_f32_dpp v158, v158, v158 quad_perm:[2,3,0,1] row_mask:0xf bank_mask:0xf
	v_add_f32_dpp v159, v159, v159 quad_perm:[2,3,0,1] row_mask:0xf bank_mask:0xf
	v_add_f32_dpp v160, v160, v160 quad_perm:[2,3,0,1] row_mask:0xf bank_mask:0xf
	v_add_f32_dpp v161, v161, v161 quad_perm:[2,3,0,1] row_mask:0xf bank_mask:0xf
	v_add_f32_dpp v98, v98, v98 row_half_mirror row_mask:0xf bank_mask:0xf
	v_add_f32_dpp v99, v99, v99 row_half_mirror row_mask:0xf bank_mask:0xf
	v_add_f32_dpp v100, v100, v100 row_half_mirror row_mask:0xf bank_mask:0xf
	v_add_f32_dpp v101, v101, v101 row_half_mirror row_mask:0xf bank_mask:0xf
	v_add_f32_dpp v102, v102, v102 row_half_mirror row_mask:0xf bank_mask:0xf
	v_add_f32_dpp v103, v103, v103 row_half_mirror row_mask:0xf bank_mask:0xf
	v_add_f32_dpp v104, v104, v104 row_half_mirror row_mask:0xf bank_mask:0xf
	v_add_f32_dpp v105, v105, v105 row_half_mirror row_mask:0xf bank_mask:0xf
	v_add_f32_dpp v106, v106, v106 row_half_mirror row_mask:0xf bank_mask:0xf
	v_add_f32_dpp v107, v107, v107 row_half_mirror row_mask:0xf bank_mask:0xf
	v_add_f32_dpp v108, v108, v108 row_half_mirror row_mask:0xf bank_mask:0xf
	v_add_f32_dpp v109, v109, v109 row_half_mirror row_mask:0xf bank_mask:0xf
	v_add_f32_dpp v110, v110, v110 row_half_mirror row_mask:0xf bank_mask:0xf
	v_add_f32_dpp v111, v111, v111 row_half_mirror row_mask:0xf bank_mask:0xf
	v_add_f32_dpp v112, v112, v112 row_half_mirror row_mask:0xf bank_mask:0xf
	v_add_f32_dpp v113, v113, v113 row_half_mirror row_mask:0xf bank_mask:0xf
	v_add_f32_dpp v114, v114, v114 row_half_mirror row_mask:0xf bank_mask:0xf
	v_add_f32_dpp v115, v115, v115 row_half_mirror row_mask:0xf bank_mask:0xf
	v_add_f32_dpp v116, v116, v116 row_half_mirror row_mask:0xf bank_mask:0xf
	v_add_f32_dpp v117, v117, v117 row_half_mirror row_mask:0xf bank_mask:0xf
	v_add_f32_dpp v118, v118, v118 row_half_mirror row_mask:0xf bank_mask:0xf
	v_add_f32_dpp v119, v119, v119 row_half_mirror row_mask:0xf bank_mask:0xf
	v_add_f32_dpp v120, v120, v120 row_half_mirror row_mask:0xf bank_mask:0xf
	v_add_f32_dpp v121, v121, v121 row_half_mirror row_mask:0xf bank_mask:0xf
	v_add_f32_dpp v122, v122, v122 row_half_mirror row_mask:0xf bank_mask:0xf
	v_add_f32_dpp v123, v123, v123 row_half_mirror row_mask:0xf bank_mask:0xf
	v_add_f32_dpp v124, v124, v124 row_half_mirror row_mask:0xf bank_mask:0xf
	v_add_f32_dpp v125, v125, v125 row_half_mirror row_mask:0xf bank_mask:0xf
	v_add_f32_dpp v126, v126, v126 row_half_mirror row_mask:0xf bank_mask:0xf
	v_add_f32_dpp v127, v127, v127 row_half_mirror row_mask:0xf bank_mask:0xf
	v_add_f32_dpp v128, v128, v128 row_half_mirror row_mask:0xf bank_mask:0xf
	v_add_f32_dpp v129, v129, v129 row_half_mirror row_mask:0xf bank_mask:0xf
	v_add_f32_dpp v130, v130, v130 row_half_mirror row_mask:0xf bank_mask:0xf
	v_add_f32_dpp v131, v131, v131 row_half_mirror row_mask:0xf bank_mask:0xf
	v_add_f32_dpp v132, v132, v132 row_half_mirror row_mask:0xf bank_mask:0xf
	v_add_f32_dpp v133, v133, v133 row_half_mirror row_mask:0xf bank_mask:0xf
	v_add_f32_dpp v134, v134, v134 row_half_mirror row_mask:0xf bank_mask:0xf
	v_add_f32_dpp v135, v135, v135 row_half_mirror row_mask:0xf bank_mask:0xf
	v_add_f32_dpp v136, v136, v136 row_half_mirror row_mask:0xf bank_mask:0xf
	v_add_f32_dpp v137, v137, v137 row_half_mirror row_mask:0xf bank_mask:0xf
	v_add_f32_dpp v138, v138, v138 row_half_mirror row_mask:0xf bank_mask:0xf
	v_add_f32_dpp v139, v139, v139 row_half_mirror row_mask:0xf bank_mask:0xf
	v_add_f32_dpp v140, v140, v140 row_half_mirror row_mask:0xf bank_mask:0xf
	v_add_f32_dpp v141, v141, v141 row_half_mirror row_mask:0xf bank_mask:0xf
	v_add_f32_dpp v142, v142, v142 row_half_mirror row_mask:0xf bank_mask:0xf
	v_add_f32_dpp v143, v143, v143 row_half_mirror row_mask:0xf bank_mask:0xf
	v_add_f32_dpp v144, v144, v144 row_half_mirror row_mask:0xf bank_mask:0xf
	v_add_f32_dpp v145, v145, v145 row_half_mirror row_mask:0xf bank_mask:0xf
	v_add_f32_dpp v146, v146, v146 row_half_mirror row_mask:0xf bank_mask:0xf
	v_add_f32_dpp v147, v147, v147 row_half_mirror row_mask:0xf bank_mask:0xf
	v_add_f32_dpp v148, v148, v148 row_half_mirror row_mask:0xf bank_mask:0xf
	v_add_f32_dpp v149, v149, v149 row_half_mirror row_mask:0xf bank_mask:0xf
	v_add_f32_dpp v150, v150, v150 row_half_mirror row_mask:0xf bank_mask:0xf
	v_add_f32_dpp v151, v151, v151 row_half_mirror row_mask:0xf bank_mask:0xf
	v_add_f32_dpp v152, v152, v152 row_half_mirror row_mask:0xf bank_mask:0xf
	v_add_f32_dpp v153, v153, v153 row_half_mirror row_mask:0xf bank_mask:0xf
	v_add_f32_dpp v154, v154, v154 row_half_mirror row_mask:0xf bank_mask:0xf
	v_add_f32_dpp v155, v155, v155 row_half_mirror row_mask:0xf bank_mask:0xf
	v_add_f32_dpp v156, v156, v156 row_half_mirror row_mask:0xf bank_mask:0xf
	v_add_f32_dpp v157, v157, v157 row_half_mirror row_mask:0xf bank_mask:0xf
	v_add_f32_dpp v158, v158, v158 row_half_mirror row_mask:0xf bank_mask:0xf
	v_add_f32_dpp v159, v159, v159 row_half_mirror row_mask:0xf bank_mask:0xf
	v_add_f32_dpp v160, v160, v160 row_half_mirror row_mask:0xf bank_mask:0xf
	v_add_f32_dpp v161, v161, v161 row_half_mirror row_mask:0xf bank_mask:0xf
	v_add_f32_dpp v98, v98, v98 row_mirror row_mask:0xf bank_mask:0xf
	v_add_f32_dpp v99, v99, v99 row_mirror row_mask:0xf bank_mask:0xf
	v_add_f32_dpp v100, v100, v100 row_mirror row_mask:0xf bank_mask:0xf
	v_add_f32_dpp v101, v101, v101 row_mirror row_mask:0xf bank_mask:0xf
	v_add_f32_dpp v102, v102, v102 row_mirror row_mask:0xf bank_mask:0xf
	v_add_f32_dpp v103, v103, v103 row_mirror row_mask:0xf bank_mask:0xf
	v_add_f32_dpp v104, v104, v104 row_mirror row_mask:0xf bank_mask:0xf
	v_add_f32_dpp v105, v105, v105 row_mirror row_mask:0xf bank_mask:0xf
	v_add_f32_dpp v106, v106, v106 row_mirror row_mask:0xf bank_mask:0xf
	v_add_f32_dpp v107, v107, v107 row_mirror row_mask:0xf bank_mask:0xf
	v_add_f32_dpp v108, v108, v108 row_mirror row_mask:0xf bank_mask:0xf
	v_add_f32_dpp v109, v109, v109 row_mirror row_mask:0xf bank_mask:0xf
	v_add_f32_dpp v110, v110, v110 row_mirror row_mask:0xf bank_mask:0xf
	v_add_f32_dpp v111, v111, v111 row_mirror row_mask:0xf bank_mask:0xf
	v_add_f32_dpp v112, v112, v112 row_mirror row_mask:0xf bank_mask:0xf
	v_add_f32_dpp v113, v113, v113 row_mirror row_mask:0xf bank_mask:0xf
	v_add_f32_dpp v114, v114, v114 row_mirror row_mask:0xf bank_mask:0xf
	v_add_f32_dpp v115, v115, v115 row_mirror row_mask:0xf bank_mask:0xf
	v_add_f32_dpp v116, v116, v116 row_mirror row_mask:0xf bank_mask:0xf
	v_add_f32_dpp v117, v117, v117 row_mirror row_mask:0xf bank_mask:0xf
	v_add_f32_dpp v118, v118, v118 row_mirror row_mask:0xf bank_mask:0xf
	v_add_f32_dpp v119, v119, v119 row_mirror row_mask:0xf bank_mask:0xf
	v_add_f32_dpp v120, v120, v120 row_mirror row_mask:0xf bank_mask:0xf
	v_add_f32_dpp v121, v121, v121 row_mirror row_mask:0xf bank_mask:0xf
	v_add_f32_dpp v122, v122, v122 row_mirror row_mask:0xf bank_mask:0xf
	v_add_f32_dpp v123, v123, v123 row_mirror row_mask:0xf bank_mask:0xf
	v_add_f32_dpp v124, v124, v124 row_mirror row_mask:0xf bank_mask:0xf
	v_add_f32_dpp v125, v125, v125 row_mirror row_mask:0xf bank_mask:0xf
	v_add_f32_dpp v126, v126, v126 row_mirror row_mask:0xf bank_mask:0xf
	v_add_f32_dpp v127, v127, v127 row_mirror row_mask:0xf bank_mask:0xf
	v_add_f32_dpp v128, v128, v128 row_mirror row_mask:0xf bank_mask:0xf
	v_add_f32_dpp v129, v129, v129 row_mirror row_mask:0xf bank_mask:0xf
	v_add_f32_dpp v130, v130, v130 row_mirror row_mask:0xf bank_mask:0xf
	v_add_f32_dpp v131, v131, v131 row_mirror row_mask:0xf bank_mask:0xf
	v_add_f32_dpp v132, v132, v132 row_mirror row_mask:0xf bank_mask:0xf
	v_add_f32_dpp v133, v133, v133 row_mirror row_mask:0xf bank_mask:0xf
	v_add_f32_dpp v134, v134, v134 row_mirror row_mask:0xf bank_mask:0xf
	v_add_f32_dpp v135, v135, v135 row_mirror row_mask:0xf bank_mask:0xf
	v_add_f32_dpp v136, v136, v136 row_mirror row_mask:0xf bank_mask:0xf
	v_add_f32_dpp v137, v137, v137 row_mirror row_mask:0xf bank_mask:0xf
	v_add_f32_dpp v138, v138, v138 row_mirror row_mask:0xf bank_mask:0xf
	v_add_f32_dpp v139, v139, v139 row_mirror row_mask:0xf bank_mask:0xf
	v_add_f32_dpp v140, v140, v140 row_mirror row_mask:0xf bank_mask:0xf
	v_add_f32_dpp v141, v141, v141 row_mirror row_mask:0xf bank_mask:0xf
	v_add_f32_dpp v142, v142, v142 row_mirror row_mask:0xf bank_mask:0xf
	v_add_f32_dpp v143, v143, v143 row_mirror row_mask:0xf bank_mask:0xf
	v_add_f32_dpp v144, v144, v144 row_mirror row_mask:0xf bank_mask:0xf
	v_add_f32_dpp v145, v145, v145 row_mirror row_mask:0xf bank_mask:0xf
	v_add_f32_dpp v146, v146, v146 row_mirror row_mask:0xf bank_mask:0xf
	v_add_f32_dpp v147, v147, v147 row_mirror row_mask:0xf bank_mask:0xf
	v_add_f32_dpp v148, v148, v148 row_mirror row_mask:0xf bank_mask:0xf
	v_add_f32_dpp v149, v149, v149 row_mirror row_mask:0xf bank_mask:0xf
	v_add_f32_dpp v150, v150, v150 row_mirror row_mask:0xf bank_mask:0xf
	v_add_f32_dpp v151, v151, v151 row_mirror row_mask:0xf bank_mask:0xf
	v_add_f32_dpp v152, v152, v152 row_mirror row_mask:0xf bank_mask:0xf
	v_add_f32_dpp v153, v153, v153 row_mirror row_mask:0xf bank_mask:0xf
	v_add_f32_dpp v154, v154, v154 row_mirror row_mask:0xf bank_mask:0xf
	v_add_f32_dpp v155, v155, v155 row_mirror row_mask:0xf bank_mask:0xf
	v_add_f32_dpp v156, v156, v156 row_mirror row_mask:0xf bank_mask:0xf
	v_add_f32_dpp v157, v157, v157 row_mirror row_mask:0xf bank_mask:0xf
	v_add_f32_dpp v158, v158, v158 row_mirror row_mask:0xf bank_mask:0xf
	v_add_f32_dpp v159, v159, v159 row_mirror row_mask:0xf bank_mask:0xf
	v_add_f32_dpp v160, v160, v160 row_mirror row_mask:0xf bank_mask:0xf
	v_add_f32_dpp v161, v161, v161 row_mirror row_mask:0xf bank_mask:0xf
	v_add_f32_dpp v98, v98, v98 row_bcast:15 row_mask:0xa bank_mask:0xf
	v_add_f32_dpp v99, v99, v99 row_bcast:15 row_mask:0xa bank_mask:0xf
	v_add_f32_dpp v100, v100, v100 row_bcast:15 row_mask:0xa bank_mask:0xf
	v_add_f32_dpp v101, v101, v101 row_bcast:15 row_mask:0xa bank_mask:0xf
	v_add_f32_dpp v102, v102, v102 row_bcast:15 row_mask:0xa bank_mask:0xf
	v_add_f32_dpp v103, v103, v103 row_bcast:15 row_mask:0xa bank_mask:0xf
	v_add_f32_dpp v104, v104, v104 row_bcast:15 row_mask:0xa bank_mask:0xf
	v_add_f32_dpp v105, v105, v105 row_bcast:15 row_mask:0xa bank_mask:0xf
	v_add_f32_dpp v106, v106, v106 row_bcast:15 row_mask:0xa bank_mask:0xf
	v_add_f32_dpp v107, v107, v107 row_bcast:15 row_mask:0xa bank_mask:0xf
	v_add_f32_dpp v108, v108, v108 row_bcast:15 row_mask:0xa bank_mask:0xf
	v_add_f32_dpp v109, v109, v109 row_bcast:15 row_mask:0xa bank_mask:0xf
	v_add_f32_dpp v110, v110, v110 row_bcast:15 row_mask:0xa bank_mask:0xf
	v_add_f32_dpp v111, v111, v111 row_bcast:15 row_mask:0xa bank_mask:0xf
	v_add_f32_dpp v112, v112, v112 row_bcast:15 row_mask:0xa bank_mask:0xf
	v_add_f32_dpp v113, v113, v113 row_bcast:15 row_mask:0xa bank_mask:0xf
	v_add_f32_dpp v114, v114, v114 row_bcast:15 row_mask:0xa bank_mask:0xf
	v_add_f32_dpp v115, v115, v115 row_bcast:15 row_mask:0xa bank_mask:0xf
	v_add_f32_dpp v116, v116, v116 row_bcast:15 row_mask:0xa bank_mask:0xf
	v_add_f32_dpp v117, v117, v117 row_bcast:15 row_mask:0xa bank_mask:0xf
	v_add_f32_dpp v118, v118, v118 row_bcast:15 row_mask:0xa bank_mask:0xf
	v_add_f32_dpp v119, v119, v119 row_bcast:15 row_mask:0xa bank_mask:0xf
	v_add_f32_dpp v120, v120, v120 row_bcast:15 row_mask:0xa bank_mask:0xf
	v_add_f32_dpp v121, v121, v121 row_bcast:15 row_mask:0xa bank_mask:0xf
	v_add_f32_dpp v122, v122, v122 row_bcast:15 row_mask:0xa bank_mask:0xf
	v_add_f32_dpp v123, v123, v123 row_bcast:15 row_mask:0xa bank_mask:0xf
	v_add_f32_dpp v124, v124, v124 row_bcast:15 row_mask:0xa bank_mask:0xf
	v_add_f32_dpp v125, v125, v125 row_bcast:15 row_mask:0xa bank_mask:0xf
	v_add_f32_dpp v126, v126, v126 row_bcast:15 row_mask:0xa bank_mask:0xf
	v_add_f32_dpp v127, v127, v127 row_bcast:15 row_mask:0xa bank_mask:0xf
	v_add_f32_dpp v128, v128, v128 row_bcast:15 row_mask:0xa bank_mask:0xf
	v_add_f32_dpp v129, v129, v129 row_bcast:15 row_mask:0xa bank_mask:0xf
	v_add_f32_dpp v130, v130, v130 row_bcast:15 row_mask:0xa bank_mask:0xf
	v_add_f32_dpp v131, v131, v131 row_bcast:15 row_mask:0xa bank_mask:0xf
	v_add_f32_dpp v132, v132, v132 row_bcast:15 row_mask:0xa bank_mask:0xf
	v_add_f32_dpp v133, v133, v133 row_bcast:15 row_mask:0xa bank_mask:0xf
	v_add_f32_dpp v134, v134, v134 row_bcast:15 row_mask:0xa bank_mask:0xf
	v_add_f32_dpp v135, v135, v135 row_bcast:15 row_mask:0xa bank_mask:0xf
	v_add_f32_dpp v136, v136, v136 row_bcast:15 row_mask:0xa bank_mask:0xf
	v_add_f32_dpp v137, v137, v137 row_bcast:15 row_mask:0xa bank_mask:0xf
	v_add_f32_dpp v138, v138, v138 row_bcast:15 row_mask:0xa bank_mask:0xf
	v_add_f32_dpp v139, v139, v139 row_bcast:15 row_mask:0xa bank_mask:0xf
	v_add_f32_dpp v140, v140, v140 row_bcast:15 row_mask:0xa bank_mask:0xf
	v_add_f32_dpp v141, v141, v141 row_bcast:15 row_mask:0xa bank_mask:0xf
	v_add_f32_dpp v142, v142, v142 row_bcast:15 row_mask:0xa bank_mask:0xf
	v_add_f32_dpp v143, v143, v143 row_bcast:15 row_mask:0xa bank_mask:0xf
	v_add_f32_dpp v144, v144, v144 row_bcast:15 row_mask:0xa bank_mask:0xf
	v_add_f32_dpp v145, v145, v145 row_bcast:15 row_mask:0xa bank_mask:0xf
	v_add_f32_dpp v146, v146, v146 row_bcast:15 row_mask:0xa bank_mask:0xf
	v_add_f32_dpp v147, v147, v147 row_bcast:15 row_mask:0xa bank_mask:0xf
	v_add_f32_dpp v148, v148, v148 row_bcast:15 row_mask:0xa bank_mask:0xf
	v_add_f32_dpp v149, v149, v149 row_bcast:15 row_mask:0xa bank_mask:0xf
	v_add_f32_dpp v150, v150, v150 row_bcast:15 row_mask:0xa bank_mask:0xf
	v_add_f32_dpp v151, v151, v151 row_bcast:15 row_mask:0xa bank_mask:0xf
	v_add_f32_dpp v152, v152, v152 row_bcast:15 row_mask:0xa bank_mask:0xf
	v_add_f32_dpp v153, v153, v153 row_bcast:15 row_mask:0xa bank_mask:0xf
	v_add_f32_dpp v154, v154, v154 row_bcast:15 row_mask:0xa bank_mask:0xf
	v_add_f32_dpp v155, v155, v155 row_bcast:15 row_mask:0xa bank_mask:0xf
	v_add_f32_dpp v156, v156, v156 row_bcast:15 row_mask:0xa bank_mask:0xf
	v_add_f32_dpp v157, v157, v157 row_bcast:15 row_mask:0xa bank_mask:0xf
	v_add_f32_dpp v158, v158, v158 row_bcast:15 row_mask:0xa bank_mask:0xf
	v_add_f32_dpp v159, v159, v159 row_bcast:15 row_mask:0xa bank_mask:0xf
	v_add_f32_dpp v160, v160, v160 row_bcast:15 row_mask:0xa bank_mask:0xf
	v_add_f32_dpp v161, v161, v161 row_bcast:15 row_mask:0xa bank_mask:0xf
	v_add_f32_dpp v98, v98, v98 row_bcast:31 row_mask:0xc bank_mask:0xf
	v_add_f32_dpp v99, v99, v99 row_bcast:31 row_mask:0xc bank_mask:0xf
	v_add_f32_dpp v100, v100, v100 row_bcast:31 row_mask:0xc bank_mask:0xf
	v_add_f32_dpp v101, v101, v101 row_bcast:31 row_mask:0xc bank_mask:0xf
	v_add_f32_dpp v102, v102, v102 row_bcast:31 row_mask:0xc bank_mask:0xf
	v_add_f32_dpp v103, v103, v103 row_bcast:31 row_mask:0xc bank_mask:0xf
	v_add_f32_dpp v104, v104, v104 row_bcast:31 row_mask:0xc bank_mask:0xf
	v_add_f32_dpp v105, v105, v105 row_bcast:31 row_mask:0xc bank_mask:0xf
	v_add_f32_dpp v106, v106, v106 row_bcast:31 row_mask:0xc bank_mask:0xf
	v_add_f32_dpp v107, v107, v107 row_bcast:31 row_mask:0xc bank_mask:0xf
	v_add_f32_dpp v108, v108, v108 row_bcast:31 row_mask:0xc bank_mask:0xf
	v_add_f32_dpp v109, v109, v109 row_bcast:31 row_mask:0xc bank_mask:0xf
	v_add_f32_dpp v110, v110, v110 row_bcast:31 row_mask:0xc bank_mask:0xf
	v_add_f32_dpp v111, v111, v111 row_bcast:31 row_mask:0xc bank_mask:0xf
	v_add_f32_dpp v112, v112, v112 row_bcast:31 row_mask:0xc bank_mask:0xf
	v_add_f32_dpp v113, v113, v113 row_bcast:31 row_mask:0xc bank_mask:0xf
	v_add_f32_dpp v114, v114, v114 row_bcast:31 row_mask:0xc bank_mask:0xf
	v_add_f32_dpp v115, v115, v115 row_bcast:31 row_mask:0xc bank_mask:0xf
	v_add_f32_dpp v116, v116, v116 row_bcast:31 row_mask:0xc bank_mask:0xf
	v_add_f32_dpp v117, v117, v117 row_bcast:31 row_mask:0xc bank_mask:0xf
	v_add_f32_dpp v118, v118, v118 row_bcast:31 row_mask:0xc bank_mask:0xf
	v_add_f32_dpp v119, v119, v119 row_bcast:31 row_mask:0xc bank_mask:0xf
	v_add_f32_dpp v120, v120, v120 row_bcast:31 row_mask:0xc bank_mask:0xf
	v_add_f32_dpp v121, v121, v121 row_bcast:31 row_mask:0xc bank_mask:0xf
	v_add_f32_dpp v122, v122, v122 row_bcast:31 row_mask:0xc bank_mask:0xf
	v_add_f32_dpp v123, v123, v123 row_bcast:31 row_mask:0xc bank_mask:0xf
	v_add_f32_dpp v124, v124, v124 row_bcast:31 row_mask:0xc bank_mask:0xf
	v_add_f32_dpp v125, v125, v125 row_bcast:31 row_mask:0xc bank_mask:0xf
	v_add_f32_dpp v126, v126, v126 row_bcast:31 row_mask:0xc bank_mask:0xf
	v_add_f32_dpp v127, v127, v127 row_bcast:31 row_mask:0xc bank_mask:0xf
	v_add_f32_dpp v128, v128, v128 row_bcast:31 row_mask:0xc bank_mask:0xf
	v_add_f32_dpp v129, v129, v129 row_bcast:31 row_mask:0xc bank_mask:0xf
	v_add_f32_dpp v130, v130, v130 row_bcast:31 row_mask:0xc bank_mask:0xf
	v_add_f32_dpp v131, v131, v131 row_bcast:31 row_mask:0xc bank_mask:0xf
	v_add_f32_dpp v132, v132, v132 row_bcast:31 row_mask:0xc bank_mask:0xf
	v_add_f32_dpp v133, v133, v133 row_bcast:31 row_mask:0xc bank_mask:0xf
	v_add_f32_dpp v134, v134, v134 row_bcast:31 row_mask:0xc bank_mask:0xf
	v_add_f32_dpp v135, v135, v135 row_bcast:31 row_mask:0xc bank_mask:0xf
	v_add_f32_dpp v136, v136, v136 row_bcast:31 row_mask:0xc bank_mask:0xf
	v_add_f32_dpp v137, v137, v137 row_bcast:31 row_mask:0xc bank_mask:0xf
	v_add_f32_dpp v138, v138, v138 row_bcast:31 row_mask:0xc bank_mask:0xf
	v_add_f32_dpp v139, v139, v139 row_bcast:31 row_mask:0xc bank_mask:0xf
	v_add_f32_dpp v140, v140, v140 row_bcast:31 row_mask:0xc bank_mask:0xf
	v_add_f32_dpp v141, v141, v141 row_bcast:31 row_mask:0xc bank_mask:0xf
	v_add_f32_dpp v142, v142, v142 row_bcast:31 row_mask:0xc bank_mask:0xf
	v_add_f32_dpp v143, v143, v143 row_bcast:31 row_mask:0xc bank_mask:0xf
	v_add_f32_dpp v144, v144, v144 row_bcast:31 row_mask:0xc bank_mask:0xf
	v_add_f32_dpp v145, v145, v145 row_bcast:31 row_mask:0xc bank_mask:0xf
	v_add_f32_dpp v146, v146, v146 row_bcast:31 row_mask:0xc bank_mask:0xf
	v_add_f32_dpp v147, v147, v147 row_bcast:31 row_mask:0xc bank_mask:0xf
	v_add_f32_dpp v148, v148, v148 row_bcast:31 row_mask:0xc bank_mask:0xf
	v_add_f32_dpp v149, v149, v149 row_bcast:31 row_mask:0xc bank_mask:0xf
	v_add_f32_dpp v150, v150, v150 row_bcast:31 row_mask:0xc bank_mask:0xf
	v_add_f32_dpp v151, v151, v151 row_bcast:31 row_mask:0xc bank_mask:0xf
	v_add_f32_dpp v152, v152, v152 row_bcast:31 row_mask:0xc bank_mask:0xf
	v_add_f32_dpp v153, v153, v153 row_bcast:31 row_mask:0xc bank_mask:0xf
	v_add_f32_dpp v154, v154, v154 row_bcast:31 row_mask:0xc bank_mask:0xf
	v_add_f32_dpp v155, v155, v155 row_bcast:31 row_mask:0xc bank_mask:0xf
	v_add_f32_dpp v156, v156, v156 row_bcast:31 row_mask:0xc bank_mask:0xf
	v_add_f32_dpp v157, v157, v157 row_bcast:31 row_mask:0xc bank_mask:0xf
	v_add_f32_dpp v158, v158, v158 row_bcast:31 row_mask:0xc bank_mask:0xf
	v_add_f32_dpp v159, v159, v159 row_bcast:31 row_mask:0xc bank_mask:0xf
	v_add_f32_dpp v160, v160, v160 row_bcast:31 row_mask:0xc bank_mask:0xf
	v_add_f32_dpp v161, v161, v161 row_bcast:31 row_mask:0xc bank_mask:0xf
	s_nop 0
	v_readlane_b32 s32, v98, 63
	v_readlane_b32 s33, v99, 63
	v_readlane_b32 s40, v100, 63
	v_readlane_b32 s41, v101, 63
	v_readlane_b32 s46, v102, 63
	v_readlane_b32 s47, v103, 63
	v_readlane_b32 s51, v104, 63
	v_readlane_b32 s57, v105, 63
	v_readlane_b32 s58, v106, 63
	v_readlane_b32 s59, v107, 63
	v_readlane_b32 s60, v108, 63
	v_readlane_b32 s61, v109, 63
	v_readlane_b32 s62, v110, 63
	v_readlane_b32 s63, v111, 63
	v_readlane_b32 s70, v112, 63
	v_readlane_b32 s71, v113, 63
	s_nop 1
	v_writelane_b32 v9, s32, 0
	v_writelane_b32 v9, s33, 1
	v_writelane_b32 v9, s40, 2
	v_writelane_b32 v9, s41, 3
	v_writelane_b32 v9, s46, 4
	v_writelane_b32 v9, s47, 5
	v_writelane_b32 v9, s51, 6
	v_writelane_b32 v9, s57, 7
	v_writelane_b32 v9, s58, 8
	v_writelane_b32 v9, s59, 9
	v_writelane_b32 v9, s60, 10
	v_writelane_b32 v9, s61, 11
	v_writelane_b32 v9, s62, 12
	v_writelane_b32 v9, s63, 13
	v_writelane_b32 v9, s70, 14
	v_writelane_b32 v9, s71, 15
	v_readlane_b32 s32, v114, 63
	v_readlane_b32 s33, v115, 63
	v_readlane_b32 s40, v116, 63
	v_readlane_b32 s41, v117, 63
	v_readlane_b32 s46, v118, 63
	v_readlane_b32 s47, v119, 63
	v_readlane_b32 s51, v120, 63
	v_readlane_b32 s57, v121, 63
	v_readlane_b32 s58, v122, 63
	v_readlane_b32 s59, v123, 63
	v_readlane_b32 s60, v124, 63
	v_readlane_b32 s61, v125, 63
	v_readlane_b32 s62, v126, 63
	v_readlane_b32 s63, v127, 63
	v_readlane_b32 s70, v128, 63
	v_readlane_b32 s71, v129, 63
	s_nop 1
	v_writelane_b32 v9, s32, 16
	v_writelane_b32 v9, s33, 17
	v_writelane_b32 v9, s40, 18
	v_writelane_b32 v9, s41, 19
	v_writelane_b32 v9, s46, 20
	v_writelane_b32 v9, s47, 21
	v_writelane_b32 v9, s51, 22
	v_writelane_b32 v9, s57, 23
	v_writelane_b32 v9, s58, 24
	v_writelane_b32 v9, s59, 25
	v_writelane_b32 v9, s60, 26
	v_writelane_b32 v9, s61, 27
	v_writelane_b32 v9, s62, 28
	v_writelane_b32 v9, s63, 29
	v_writelane_b32 v9, s70, 30
	v_writelane_b32 v9, s71, 31
	v_readlane_b32 s32, v130, 63
	v_readlane_b32 s33, v131, 63
	v_readlane_b32 s40, v132, 63
	v_readlane_b32 s41, v133, 63
	v_readlane_b32 s46, v134, 63
	v_readlane_b32 s47, v135, 63
	v_readlane_b32 s51, v136, 63
	v_readlane_b32 s57, v137, 63
	v_readlane_b32 s58, v138, 63
	v_readlane_b32 s59, v139, 63
	v_readlane_b32 s60, v140, 63
	v_readlane_b32 s61, v141, 63
	v_readlane_b32 s62, v142, 63
	v_readlane_b32 s63, v143, 63
	v_readlane_b32 s70, v144, 63
	v_readlane_b32 s71, v145, 63
	s_nop 1
	v_writelane_b32 v9, s32, 32
	v_writelane_b32 v9, s33, 33
	v_writelane_b32 v9, s40, 34
	v_writelane_b32 v9, s41, 35
	v_writelane_b32 v9, s46, 36
	v_writelane_b32 v9, s47, 37
	v_writelane_b32 v9, s51, 38
	v_writelane_b32 v9, s57, 39
	v_writelane_b32 v9, s58, 40
	v_writelane_b32 v9, s59, 41
	v_writelane_b32 v9, s60, 42
	v_writelane_b32 v9, s61, 43
	v_writelane_b32 v9, s62, 44
	v_writelane_b32 v9, s63, 45
	v_writelane_b32 v9, s70, 46
	v_writelane_b32 v9, s71, 47
	v_readlane_b32 s32, v146, 63
	v_readlane_b32 s33, v147, 63
	v_readlane_b32 s40, v148, 63
	v_readlane_b32 s41, v149, 63
	v_readlane_b32 s46, v150, 63
	v_readlane_b32 s47, v151, 63
	v_readlane_b32 s51, v152, 63
	v_readlane_b32 s57, v153, 63
	v_readlane_b32 s58, v154, 63
	v_readlane_b32 s59, v155, 63
	v_readlane_b32 s60, v156, 63
	v_readlane_b32 s61, v157, 63
	v_readlane_b32 s62, v158, 63
	v_readlane_b32 s63, v159, 63
	v_readlane_b32 s70, v160, 63
	v_readlane_b32 s71, v161, 63
	s_nop 1
	v_writelane_b32 v9, s32, 48
	v_writelane_b32 v9, s33, 49
	v_writelane_b32 v9, s40, 50
	v_writelane_b32 v9, s41, 51
	v_writelane_b32 v9, s46, 52
	v_writelane_b32 v9, s47, 53
	v_writelane_b32 v9, s51, 54
	v_writelane_b32 v9, s57, 55
	v_writelane_b32 v9, s58, 56
	v_writelane_b32 v9, s59, 57
	v_writelane_b32 v9, s60, 58
	v_writelane_b32 v9, s61, 59
	v_writelane_b32 v9, s62, 60
	v_writelane_b32 v9, s63, 61
	v_writelane_b32 v9, s70, 62
	v_writelane_b32 v9, s71, 63
	v_lshrrev_b32_e32 v10, 2, v0
	v_and_b32_e32 v11, 3, v0
	v_mul_lo_u32 v10, v10, s23
	v_add3_u32 v15, v10, v11, s91
	v_lshlrev_b32_e32 v15, 2, v15
	s_add_u32 s8, s0, s22
	s_addc_u32 s9, s1, 0
	global_store_dword v15, v9, s[8:9] sc1
	s_branch .LBB0_477
.Lcv7_idle:
	s_waitcnt vmcnt(0)
	s_lshl_b32 s8, s3, 8
	s_add_u32 s8, s0, s8
	s_addc_u32 s9, s1, 0
	v_mov_b32_e32 v15, 0
	v_mov_b32_e32 v11, 1
	s_mov_b64 exec, 1
	global_atomic_add v15, v11, s[8:9] offset:2112
	s_mov_b64 exec, -1
.LBB0_477:
	v_mbcnt_lo_u32_b32 v0, -1, 0
	v_mbcnt_hi_u32_b32 v0, -1, v0
	s_waitcnt vmcnt(0)
	v_readlane_b32 s0, v254, 8
	v_readlane_b32 s1, v254, 9
	v_mov_b32_e32 v4, 0
	v_mov_b32_e32 v5, 1
	s_mov_b64 exec, 1
	s_nop 3
	global_atomic_add v4, v5, s[0:1] offset:2176
	s_mov_b64 exec, -1
	s_waitcnt lgkmcnt(0)
	v_or_b32_e32 v0, s89, v0
	v_cmp_eq_u32_e32 vcc, 0, v0
	s_barrier
	s_and_saveexec_b64 s[0:1], vcc
	s_cbranch_execz .LBB0_529
	s_add_i32 s2, 0, 0x22028
	v_mov_b32_e32 v0, s2
	s_waitcnt vmcnt(0) expcnt(0) lgkmcnt(0)
	ds_read_b32 v2, v0
	s_add_i32 s2, 0, 0x2202c
	v_mov_b32_e32 v0, s2
	ds_read_b32 v0, v0
	s_waitcnt lgkmcnt(1)
	v_cmp_ne_u32_e32 vcc, 0, v2
	s_cbranch_vccnz .LBB0_493
	s_add_u32 s2, s66, 0x1000
	s_addc_u32 s3, s67, 0
	s_add_u32 s4, s66, 0x1100
	s_addc_u32 s5, s67, 0
	s_add_u32 s8, s66, 0x1200
	s_addc_u32 s9, s67, 0
	s_add_u32 s22, s66, 0x1300
	s_addc_u32 s23, s67, 0
	s_mov_b32 s10, 1
	v_mov_b32_e32 v16, 0
	s_branch .LBB0_481

.LBB0_695:
	s_or_b64 exec, exec, s[0:1]
	v_readlane_b32 s2, v254, 8
	v_readlane_b32 s3, v254, 9
	v_mov_b32_e32 v4, 0
	s_nop 3
.Lgcv_poll:
	global_load_dword v5, v4, s[2:3] offset:2176 sc1
	s_waitcnt vmcnt(0)
	v_readfirstlane_b32 s4, v5
	s_cmpk_lt_u32 s4, 0x800
	s_cbranch_scc1 .Lgcv_poll
	buffer_inv sc1
	s_waitcnt vmcnt(0)
	v_readlane_b32 s0, v254, 8
	v_readlane_b32 s1, v254, 9
	s_add_u32 s34, s0, 0xa00000
	s_addc_u32 s35, s1, 0
	s_add_u32 s36, s0, 0xc00000
	v_readlane_b32 s2, v254, 10
	s_addc_u32 s37, s1, 0
	v_readlane_b32 s3, v254, 11
	s_add_u32 s2, s0, 0xc000000
	s_addc_u32 s3, s1, 0
	s_add_u32 s26, s0, 0xe000000
	s_addc_u32 s27, s1, 0
	s_add_u32 s12, s0, 0xf800000
	v_writelane_b32 v254, s2, 56
	s_addc_u32 s13, s1, 0
	s_waitcnt lgkmcnt(0)
	v_writelane_b32 v254, s3, 57
	s_add_u32 s2, s0, 0x10800000
	s_addc_u32 s3, s1, 0
	v_writelane_b32 v254, s2, 58
	s_add_u32 s30, s0, 0xe00000
	s_addc_u32 s31, s1, 0
	v_writelane_b32 v254, s3, 59
	v_writelane_b32 v254, s58, 60
	s_add_u32 s24, s0, 0xf00000
	s_barrier
	v_writelane_b32 v254, s59, 61
	v_writelane_b32 v254, s61, 62
	v_writelane_b32 v254, s62, 63
	s_addc_u32 s25, s1, 0
	v_mbcnt_lo_u32_b32 v0, -1, 0
	v_mbcnt_hi_u32_b32 v0, -1, v0
	v_writelane_b32 v255, s60, 0
	v_or_b32_e32 v14, s89, v0
	v_writelane_b32 v254, s76, 36
	s_cmpk_lt_i32 s86, 0x480
	v_writelane_b32 v255, s73, 1
	v_readfirstlane_b32 s9, v14
	v_writelane_b32 v254, s77, 37
	s_cbranch_scc0 .LBB0_790
	s_movk_i32 s29, 0x91
	s_and_b64 s[0:1], s[22:23], exec
	v_lshlrev_b32_e32 v0, 4, v14
	s_cselect_b32 s0, s29, 0x90
	v_add_u32_e32 v1, 0x2000, v0
	s_mul_i32 s0, s0, s62
	v_ashrrev_i32_e32 v2, 31, v1
	s_add_i32 s0, s0, s61
	v_lshrrev_b32_e32 v2, 22, v2
	s_mul_hi_i32 s1, s0, 0x38e38e39
	v_add_u32_e32 v2, v1, v2
	s_lshr_b32 s2, s1, 31
	s_ashr_i32 s1, s1, 4
	v_ashrrev_i32_e32 v8, 10, v2
	s_add_i32 s1, s1, s2
	v_mul_i32_i24_e32 v2, 0x400, v8
	s_lshl_b32 s2, s1, 3
	s_mulk_i32 s1, 0x48
	v_sub_u32_e32 v1, v1, v2
	s_sub_i32 s0, s0, s1
	v_lshrrev_b32_e32 v2, 4, v1
	s_bfe_i32 s1, s0, 0x80000
	v_bitop3_b32 v1, v2, v1, 32 bitop3:0x6c
	s_bfe_u32 s1, s1, 0x3000c
	v_ashrrev_i32_e32 v2, 31, v1
	s_add_i32 s1, s0, s1
	v_lshrrev_b32_e32 v2, 26, v2
	s_bfe_i32 s3, s1, 0x80000
	s_and_b32 s1, s1, 0xf8
	v_add_u32_e32 v2, v1, v2
	v_lshlrev_b32_e32 v3, 3, v8
	s_sub_i32 s0, s0, s1
	v_ashrrev_i32_e32 v9, 6, v2
	v_and_b32_e32 v3, -16, v3
	s_sext_i32_i8 s0, s0
	v_add_u32_e32 v3, v9, v3
	s_add_i32 s2, s2, s0
	v_and_b32_e32 v4, 3, v9
	s_mov_b32 s0, 0x1fffe0
	v_lshrrev_b32_e32 v5, 2, v3
	v_lshlrev_b32_e32 v6, 1, v3
	v_and_b32_e32 v2, 0xc0, v2
	v_and_or_b32 v4, v3, s0, v4
	v_and_b32_e32 v5, 4, v5
	v_and_b32_e32 v6, 24, v6
	v_sub_u32_e32 v1, v1, v2
	v_mov_b32_e32 v2, 1
	v_or3_b32 v4, v4, v5, v6
	v_lshlrev_b32_e32 v5, 5, v8
	v_ashrrev_i16_sdwa v1, v2, sext(v1) dst_sel:DWORD dst_unused:UNUSED_PAD src0_sel:DWORD src1_sel:BYTE_0
	v_and_b32_e32 v5, 32, v5
	v_bfe_i32 v10, v1, 0, 16
	v_add_lshl_u32 v1, v5, v10, 1
	v_lshl_add_u32 v152, v4, 11, v1
	v_lshl_add_u32 v154, v3, 11, v1
	v_bfe_i32 v1, v14, 27, 1
	v_lshrrev_b32_e32 v1, 22, v1
	v_add_u32_e32 v1, v0, v1
	v_and_b32_e32 v1, 0xfffffc00, v1
	v_sub_u32_e32 v0, v0, v1
	v_lshrrev_b32_e32 v1, 4, v0
	v_ashrrev_i32_e32 v3, 31, v14
	v_bitop3_b32 v0, v1, v0, 32 bitop3:0x6c
	v_lshrrev_b32_e32 v3, 26, v3
	v_ashrrev_i32_e32 v1, 31, v0
	v_add_u32_e32 v3, v14, v3
	v_lshrrev_b32_e32 v1, 26, v1
	v_ashrrev_i32_e32 v12, 6, v3
	v_add_u32_e32 v1, v0, v1
	v_lshlrev_b32_e32 v3, 3, v12
	v_ashrrev_i32_e32 v11, 6, v1
	v_and_b32_e32 v3, -16, v3
	s_sext_i32_i16 s3, s3
	v_add_u32_e32 v3, v11, v3
	s_lshr_b32 s8, s3, 3
	v_and_b32_e32 v4, 3, v11
	v_lshrrev_b32_e32 v5, 2, v3
	v_lshlrev_b32_e32 v6, 1, v3
	v_and_b32_e32 v1, 0xc0, v1
	s_ashr_i32 s14, s9, 6
	v_and_or_b32 v4, v3, s0, v4
	v_and_b32_e32 v5, 4, v5
	v_and_b32_e32 v6, 24, v6
	v_sub_u32_e32 v0, v0, v1
	s_ashr_i32 s3, s2, 31
	s_bfe_i64 s[4:5], s[8:9], 0x100000
	s_ashr_i32 s11, s9, 8
	s_lshl_b32 s33, s14, 10
	v_or3_b32 v4, v4, v5, v6
	v_lshlrev_b32_e32 v5, 5, v12
	v_ashrrev_i16_sdwa v0, v2, sext(v0) dst_sel:DWORD dst_unused:UNUSED_PAD src0_sel:DWORD src1_sel:BYTE_0
	s_lshl_b64 s[0:1], s[2:3], 19
	s_lshl_b64 s[4:5], s[4:5], 19
	v_and_b32_e32 v5, 32, v5
	v_bfe_i32 v13, v0, 0, 16
	s_add_u32 s6, s20, s4
	v_add_lshl_u32 v0, v5, v13, 1
	s_addc_u32 s7, s21, s5
	s_add_i32 s64, s33, 0
	v_lshl_add_u32 v156, v4, 11, v0
	s_add_i32 m0, s64, 0x10000
	v_lshl_add_u32 v158, v3, 11, v0
	global_load_lds_dwordx4 v156, s[6:7]
	s_add_i32 m0, s64, 0x12000
	s_add_u32 s4, s6, 0x40000
	global_load_lds_dwordx4 v152, s[6:7]
	s_addc_u32 s5, s7, 0
	s_add_i32 m0, s64, 0x14000
	v_mov_b32_e32 v157, 0
	global_load_lds_dwordx4 v156, s[4:5]
	s_add_i32 m0, s64, 0x16000
	v_writelane_b32 v254, s78, 30
	global_load_lds_dwordx4 v152, s[4:5]
	s_add_u32 s4, s76, s0
	s_addc_u32 s5, s77, s1
	s_add_i32 s65, s64, 0x2000
	s_mov_b32 m0, s64
	s_add_u32 s0, s4, 0x40000
	global_load_lds_dwordx4 v158, s[4:5]
	s_mov_b32 m0, s65
	s_addc_u32 s1, s5, 0
	s_add_i32 s66, s64, 0x4000
	global_load_lds_dwordx4 v154, s[4:5]
	s_mov_b32 m0, s66
	s_add_i32 s67, s64, 0x6000
	global_load_lds_dwordx4 v158, s[0:1]
	s_mov_b32 m0, s67
	v_mov_b32_e32 v153, v157
	global_load_lds_dwordx4 v154, s[0:1]
	v_mov_b32_e32 v159, v157
	v_mov_b32_e32 v155, v157
	s_cmp_eq_u32 s11, 1
	v_writelane_b32 v254, s79, 31
	s_mov_b64 s[94:95], s[74:75]
	s_mov_b64 s[92:93], s[70:71]
	s_mov_b32 s91, s72
	s_mov_b32 s70, 0
	v_lshl_add_u64 v[6:7], s[6:7], 0, v[156:157]
	v_lshl_add_u64 v[4:5], s[6:7], 0, v[152:153]
	v_lshl_add_u64 v[0:1], s[4:5], 0, v[158:159]
	s_cselect_b64 s[0:1], -1, 0
	s_cmp_lg_u32 s11, 1
	v_lshl_add_u64 v[2:3], s[4:5], 0, v[154:155]
	s_cbranch_scc1 .LBB0_698
	s_barrier
